# s_setprio lever: GEMM K-loop load segments run at priority 2 (MFMA segments stay at 1), on top of r1
# speedup vs baseline: 1.0064x; 1.0064x over previous
; #define PG8_STAGE(bufoff, gbase, voff) do { if constexpr (DIAG >= 1) break; _Pragma("unroll") for (int _i = 0; _i < 2; ++_i) \
;         __builtin_amdgcn_global_load_lds((const unsigned*)((const char*)(gbase) + (voff)[_i]), (PG8_LAS unsigned*)(lds + (bufoff) + ldsw + _i * 8192), 16, 0, 0); } while (0)
; #define PG8_LDA(dst, b, h) do { if constexpr (DIAG == 2 || DIAG == 3) break; _Pragma("unroll") for (int m = 0; m < 4; ++m) _Pragma("unroll") for (int k = 0; k < 2; ++k) dst[m][k] = *(const PG8_LAS bf16x8*)(lds + PG8_SA(b, h) + aoff + m * 2048 + k * 1024); } while (0)
; #define PG8_LDB(dst, b, h) do { if constexpr (DIAG == 2 || DIAG == 3) break; _Pragma("unroll") for (int n = 0; n < 2; ++n) _Pragma("unroll") for (int k = 0; k < 2; ++k) dst[n][k] = *(const PG8_LAS bf16x8*)(lds + PG8_SB(b, h) + boff + n * 2048 + k * 1024); } while (0)
; #define PG8_WAIT_V(n) asm volatile("s_waitcnt vmcnt(" #n ")" ::: "memory")
; #define PG8_WAIT_L(n) asm volatile("s_waitcnt lgkmcnt(" #n ")" ::: "memory")
; #define PG8_BAR __builtin_amdgcn_s_barrier()
; #define PG8_LP_ON __builtin_amdgcn_s_setprio(PG8_LOADPRIO)
; #define PG8_LP_OFF __builtin_amdgcn_s_setprio(0)
; #define PG8_LP_ON do {} while (0)
; #define PG8_LP_OFF do {} while (0)
; #define PG8_SCHED __builtin_amdgcn_sched_barrier(0)
;     ...
;             PG8_LP_ON; PG8_LDB(B0, 0, 0); PG8_LDB(B1, 0, 1); PG8_SCHED; PG8_LDA(At, 0, 0); PG8_STAGE(PG8_SA(1, 1), a1 + hstep, voffA);
;             PG8_LP_OFF; PG8_WAIT_V(8); PG8_WAIT_L(0); PG8_BAR; PG8_MMA(0, 0, At, B0); PG8_MMA(0, 1, At, B1); PG8_BAR; PG8_SCHED;
;             PG8_LP_ON; PG8_LDA(At, 0, 1); PG8_STAGE(PG8_SB(0, 0), b2, voffB); PG8_STAGE(PG8_SB(0, 1), b2 + hstep, voffB); PG8_STAGE(PG8_SA(0, 0), a2, voffA);
;             PG8_LP_OFF; PG8_WAIT_V(8); PG8_WAIT_L(0); PG8_BAR; PG8_MMA(1, 0, At, B0); PG8_MMA(1, 1, At, B1); PG8_BAR; PG8_SCHED;
.LBB0_225:
	ds_read_b128 v[26:29], v192
	ds_read_b128 v[30:33], v192 offset:1024
	ds_read_b128 v[18:21], v192 offset:2048
	ds_read_b128 v[22:25], v192 offset:3072
	ds_read_b128 v[10:13], v193
	ds_read_b128 v[14:17], v193 offset:1024
	ds_read_b128 v[2:5], v193 offset:2048
	ds_read_b128 v[6:9], v193 offset:3072
	s_add_u32 s77, s86, 0xfff80080
	s_addc_u32 s78, s87, -1
	s_cmp_eq_u32 s76, 28
	s_cselect_b32 s91, s23, s78
	s_cselect_b32 s90, vcc_lo, s77
	s_cselect_b32 s89, s21, s75
	s_cselect_b32 s88, vcc_hi, s74
	v_lshl_add_u64 v[220:221], s[86:87], 0, v[174:175]
	s_add_i32 m0, s19, 0xc000
	ds_read_b128 v[182:185], v194
	ds_read_b128 v[186:189], v194 offset:1024
	ds_read_b128 v[196:199], v194 offset:2048
	ds_read_b128 v[200:203], v194 offset:3072
	ds_read_b128 v[204:207], v194 offset:4096
	ds_read_b128 v[208:211], v194 offset:5120
	ds_read_b128 v[212:215], v194 offset:6144
	ds_read_b128 v[216:219], v194 offset:7168
	global_load_lds_dwordx4 v[220:221], off
	v_lshl_add_u64 v[220:221], s[86:87], 0, v[176:177]
	s_add_i32 m0, s19, 0xe000
	s_nop 0
	global_load_lds_dwordx4 v[220:221], off
	s_waitcnt vmcnt(8)
	s_waitcnt lgkmcnt(0)
	s_barrier
	s_setprio 1
	s_waitcnt lgkmcnt(0)
	v_mfma_f32_16x16x128_f8f6f4 v[158:161], v[26:33], v[182:189], v[158:161]
	v_mfma_f32_16x16x128_f8f6f4 v[154:157], v[18:25], v[182:189], v[154:157]
	v_mfma_f32_16x16x128_f8f6f4 v[142:145], v[26:33], v[196:203], v[142:145]
	v_mfma_f32_16x16x128_f8f6f4 v[138:141], v[18:25], v[196:203], v[138:141]
	v_mfma_f32_16x16x128_f8f6f4 v[126:129], v[26:33], v[204:211], v[126:129]
	v_mfma_f32_16x16x128_f8f6f4 v[122:125], v[18:25], v[204:211], v[122:125]
	v_mfma_f32_16x16x128_f8f6f4 v[110:113], v[26:33], v[212:219], v[110:113]
	v_mfma_f32_16x16x128_f8f6f4 v[106:109], v[18:25], v[212:219], v[106:109]
	s_setprio 0
	s_setprio 1
	v_mfma_f32_16x16x128_f8f6f4 v[150:153], v[10:17], v[182:189], v[150:153]
	v_mfma_f32_16x16x128_f8f6f4 v[146:149], v[2:9], v[182:189], v[146:149]
	v_mfma_f32_16x16x128_f8f6f4 v[134:137], v[10:17], v[196:203], v[134:137]
	v_mfma_f32_16x16x128_f8f6f4 v[130:133], v[2:9], v[196:203], v[130:133]
	v_mfma_f32_16x16x128_f8f6f4 v[118:121], v[10:17], v[204:211], v[118:121]
	v_mfma_f32_16x16x128_f8f6f4 v[114:117], v[2:9], v[204:211], v[114:117]
	v_mfma_f32_16x16x128_f8f6f4 v[102:105], v[10:17], v[212:219], v[102:105]
	v_mfma_f32_16x16x128_f8f6f4 v[98:101], v[2:9], v[212:219], v[98:101]
	s_setprio 2
	s_barrier
	s_add_i32 s77, s95, s0
	v_lshl_add_u64 v[182:183], s[88:89], 0, v[168:169]
	s_mov_b32 m0, s77
	ds_read_b128 v[196:199], v194 offset:16384
	ds_read_b128 v[200:203], v194 offset:17408
	ds_read_b128 v[204:207], v194 offset:18432
	ds_read_b128 v[208:211], v194 offset:19456
	ds_read_b128 v[212:215], v194 offset:20480
	ds_read_b128 v[216:219], v194 offset:21504
	ds_read_b128 v[220:223], v194 offset:22528
	ds_read_b128 v[224:227], v194 offset:23552
	global_load_lds_dwordx4 v[182:183], off
	s_add_i32 m0, s77, 0x2000
	s_add_u32 s78, s88, 0x80000
	v_lshl_add_u64 v[184:185], s[88:89], 0, v[172:173]
	s_addc_u32 s79, s89, 0
	s_add_i32 s77, s96, s0
	global_load_lds_dwordx4 v[184:185], off
	v_lshl_add_u64 v[186:187], s[78:79], 0, v[168:169]
	s_mov_b32 m0, s77
	v_lshl_add_u64 v[188:189], s[90:91], 0, v[170:171]
	global_load_lds_dwordx4 v[186:187], off
	v_lshl_add_u64 v[186:187], s[78:79], 0, v[172:173]
	s_add_i32 m0, s77, 0x2000
	s_nop 0
	global_load_lds_dwordx4 v[186:187], off
	v_lshl_add_u64 v[186:187], s[90:91], 0, v[166:167]
	s_mov_b32 m0, s19
	s_nop 0
	global_load_lds_dwordx4 v[186:187], off
	s_mov_b32 m0, s34
	s_nop 0
	global_load_lds_dwordx4 v[188:189], off
	s_waitcnt vmcnt(8)
	s_waitcnt lgkmcnt(0)
	s_barrier
	s_setprio 1
	s_waitcnt lgkmcnt(0)
	v_mfma_f32_16x16x128_f8f6f4 v[94:97], v[26:33], v[196:203], v[94:97]
	v_mfma_f32_16x16x128_f8f6f4 v[90:93], v[18:25], v[196:203], v[90:93]
	v_mfma_f32_16x16x128_f8f6f4 v[78:81], v[26:33], v[204:211], v[78:81]
	v_mfma_f32_16x16x128_f8f6f4 v[74:77], v[18:25], v[204:211], v[74:77]
	v_mfma_f32_16x16x128_f8f6f4 v[62:65], v[26:33], v[212:219], v[62:65]
	v_mfma_f32_16x16x128_f8f6f4 v[58:61], v[18:25], v[212:219], v[58:61]
	v_mfma_f32_16x16x128_f8f6f4 v[46:49], v[26:33], v[220:227], v[46:49]
	v_mfma_f32_16x16x128_f8f6f4 v[42:45], v[18:25], v[220:227], v[42:45]
	s_setprio 0
	s_setprio 1
	v_mfma_f32_16x16x128_f8f6f4 v[86:89], v[10:17], v[196:203], v[86:89]
	v_mfma_f32_16x16x128_f8f6f4 v[82:85], v[2:9], v[196:203], v[82:85]
	v_mfma_f32_16x16x128_f8f6f4 v[70:73], v[10:17], v[204:211], v[70:73]
	v_mfma_f32_16x16x128_f8f6f4 v[66:69], v[2:9], v[204:211], v[66:69]
	v_mfma_f32_16x16x128_f8f6f4 v[54:57], v[10:17], v[212:219], v[54:57]
	v_mfma_f32_16x16x128_f8f6f4 v[50:53], v[2:9], v[212:219], v[50:53]
	v_mfma_f32_16x16x128_f8f6f4 v[38:41], v[10:17], v[220:227], v[38:41]
	v_mfma_f32_16x16x128_f8f6f4 v[34:37], v[2:9], v[220:227], v[34:37]
	s_setprio 2
	s_barrier
; #define PG8_STAGE(bufoff, gbase, voff) do { if constexpr (DIAG >= 1) break; _Pragma("unroll") for (int _i = 0; _i < 2; ++_i) \
;         __builtin_amdgcn_global_load_lds((const unsigned*)((const char*)(gbase) + (voff)[_i]), (PG8_LAS unsigned*)(lds + (bufoff) + ldsw + _i * 8192), 16, 0, 0); } while (0)
; #define PG8_LDA(dst, b, h) do { if constexpr (DIAG == 2 || DIAG == 3) break; _Pragma("unroll") for (int m = 0; m < 4; ++m) _Pragma("unroll") for (int k = 0; k < 2; ++k) dst[m][k] = *(const PG8_LAS bf16x8*)(lds + PG8_SA(b, h) + aoff + m * 2048 + k * 1024); } while (0)
; #define PG8_LDB(dst, b, h) do { if constexpr (DIAG == 2 || DIAG == 3) break; _Pragma("unroll") for (int n = 0; n < 2; ++n) _Pragma("unroll") for (int k = 0; k < 2; ++k) dst[n][k] = *(const PG8_LAS bf16x8*)(lds + PG8_SB(b, h) + boff + n * 2048 + k * 1024); } while (0)
; #define PG8_WAIT_V(n) asm volatile("s_waitcnt vmcnt(" #n ")" ::: "memory")
; #define PG8_WAIT_L(n) asm volatile("s_waitcnt lgkmcnt(" #n ")" ::: "memory")
; #define PG8_BAR __builtin_amdgcn_s_barrier()
; #define PG8_LP_ON __builtin_amdgcn_s_setprio(PG8_LOADPRIO)
; #define PG8_LP_OFF __builtin_amdgcn_s_setprio(0)
; #define PG8_LP_ON do {} while (0)
; #define PG8_LP_OFF do {} while (0)
; #define PG8_SCHED __builtin_amdgcn_sched_barrier(0)
;     ...
;             PG8_LP_ON; PG8_LDB(B0, 1, 0); PG8_LDB(B1, 1, 1); PG8_SCHED; PG8_LDA(At, 1, 0); PG8_STAGE(PG8_SA(0, 1), a2 + hstep, voffA);
;             PG8_LP_OFF; PG8_WAIT_V(8); PG8_WAIT_L(0); PG8_BAR; PG8_MMA(0, 0, At, B0); PG8_MMA(0, 1, At, B1); PG8_BAR; PG8_SCHED;
;             PG8_LP_ON; PG8_LDA(At, 1, 1); PG8_STAGE(PG8_SB(1, 0), b3, voffB); PG8_STAGE(PG8_SB(1, 1), b3 + hstep, voffB); PG8_STAGE(PG8_SA(1, 0), a3, voffA);
;             PG8_LP_OFF; PG8_WAIT_V(8); PG8_WAIT_L(0); PG8_BAR; PG8_MMA(1, 0, At, B0); PG8_MMA(1, 1, At, B1); PG8_BAR; PG8_SCHED;
	s_add_i32 s77, 0, 0x18000
	s_add_i32 s80, 0, 0x1c000
	v_add_u32_e32 v14, s77, v190
	v_add_u32_e32 v30, s80, v190
	ds_read_b128 v[2:5], v14
	ds_read_b128 v[6:9], v14 offset:1024
	ds_read_b128 v[10:13], v14 offset:2048
	ds_read_b128 v[14:17], v14 offset:3072
	ds_read_b128 v[18:21], v30
	ds_read_b128 v[22:25], v30 offset:1024
	ds_read_b128 v[26:29], v30 offset:2048
	ds_read_b128 v[30:33], v30 offset:3072
	s_add_u32 s78, s90, 0x80000
	s_addc_u32 s79, s91, 0
	s_mov_b32 m0, s73
	v_lshl_add_u64 v[228:229], s[78:79], 0, v[166:167]
	ds_read_b128 v[196:199], v194 offset:32768
	ds_read_b128 v[200:203], v194 offset:33792
	ds_read_b128 v[204:207], v194 offset:34816
	ds_read_b128 v[208:211], v194 offset:35840
	ds_read_b128 v[212:215], v194 offset:36864
	ds_read_b128 v[216:219], v194 offset:37888
	ds_read_b128 v[220:223], v194 offset:38912
	ds_read_b128 v[224:227], v194 offset:39936
	global_load_lds_dwordx4 v[228:229], off
	v_lshl_add_u64 v[228:229], s[78:79], 0, v[170:171]
	s_mov_b32 m0, s84
	s_nop 0
	global_load_lds_dwordx4 v[228:229], off
	s_waitcnt vmcnt(8)
	s_waitcnt lgkmcnt(0)
	s_barrier
	s_setprio 1
	s_waitcnt lgkmcnt(0)
	v_mfma_f32_16x16x128_f8f6f4 v[158:161], v[2:9], v[196:203], v[158:161]
	v_mfma_f32_16x16x128_f8f6f4 v[154:157], v[10:17], v[196:203], v[154:157]
	v_mfma_f32_16x16x128_f8f6f4 v[142:145], v[2:9], v[204:211], v[142:145]
	v_mfma_f32_16x16x128_f8f6f4 v[138:141], v[10:17], v[204:211], v[138:141]
	v_mfma_f32_16x16x128_f8f6f4 v[126:129], v[2:9], v[212:219], v[126:129]
	v_mfma_f32_16x16x128_f8f6f4 v[122:125], v[10:17], v[212:219], v[122:125]
	v_mfma_f32_16x16x128_f8f6f4 v[110:113], v[2:9], v[220:227], v[110:113]
	v_mfma_f32_16x16x128_f8f6f4 v[106:109], v[10:17], v[220:227], v[106:109]
	s_setprio 0
	s_setprio 1
	v_mfma_f32_16x16x128_f8f6f4 v[150:153], v[18:25], v[196:203], v[150:153]
	v_mfma_f32_16x16x128_f8f6f4 v[146:149], v[26:33], v[196:203], v[146:149]
	v_mfma_f32_16x16x128_f8f6f4 v[134:137], v[18:25], v[204:211], v[134:137]
	v_mfma_f32_16x16x128_f8f6f4 v[130:133], v[26:33], v[204:211], v[130:133]
	v_mfma_f32_16x16x128_f8f6f4 v[118:121], v[18:25], v[212:219], v[118:121]
	v_mfma_f32_16x16x128_f8f6f4 v[114:117], v[26:33], v[212:219], v[114:117]
	v_mfma_f32_16x16x128_f8f6f4 v[102:105], v[18:25], v[220:227], v[102:105]
	v_mfma_f32_16x16x128_f8f6f4 v[98:101], v[26:33], v[220:227], v[98:101]
	s_setprio 2
	s_barrier
	s_add_i32 s77, s77, s0
	v_lshl_add_u64 v[182:183], v[182:183], 0, s[12:13]
	s_mov_b32 m0, s77
	ds_read_b128 v[196:199], v194 offset:49152
	ds_read_b128 v[200:203], v194 offset:50176
	ds_read_b128 v[204:207], v194 offset:51200
	ds_read_b128 v[208:211], v194 offset:52224
	ds_read_b128 v[212:215], v194 offset:53248
	ds_read_b128 v[216:219], v194 offset:54272
	ds_read_b128 v[220:223], v194 offset:55296
	ds_read_b128 v[224:227], v194 offset:56320
	global_load_lds_dwordx4 v[182:183], off
	s_add_i32 m0, s77, 0x2000
	s_add_u32 s78, s88, 0x80080
	v_lshl_add_u64 v[182:183], v[184:185], 0, s[12:13]
	s_addc_u32 s79, s89, 0
	s_add_i32 s77, s80, s0
	global_load_lds_dwordx4 v[182:183], off
	v_lshl_add_u64 v[182:183], s[78:79], 0, v[168:169]
	s_mov_b32 m0, s77
	s_nop 0
	global_load_lds_dwordx4 v[182:183], off
	v_lshl_add_u64 v[182:183], s[78:79], 0, v[172:173]
	s_add_i32 m0, s77, 0x2000
	s_nop 0
	global_load_lds_dwordx4 v[182:183], off
	v_lshl_add_u64 v[182:183], v[186:187], 0, s[12:13]
	s_mov_b32 m0, s93
	s_nop 0
	global_load_lds_dwordx4 v[182:183], off
	v_lshl_add_u64 v[182:183], v[188:189], 0, s[12:13]
	s_mov_b32 m0, s94
	s_nop 0
	global_load_lds_dwordx4 v[182:183], off
	s_waitcnt vmcnt(8)
	s_waitcnt lgkmcnt(0)
	s_barrier
	s_setprio 1
	s_waitcnt lgkmcnt(0)
	v_mfma_f32_16x16x128_f8f6f4 v[94:97], v[2:9], v[196:203], v[94:97]
	v_mfma_f32_16x16x128_f8f6f4 v[90:93], v[10:17], v[196:203], v[90:93]
	v_mfma_f32_16x16x128_f8f6f4 v[78:81], v[2:9], v[204:211], v[78:81]
	v_mfma_f32_16x16x128_f8f6f4 v[74:77], v[10:17], v[204:211], v[74:77]
	v_mfma_f32_16x16x128_f8f6f4 v[62:65], v[2:9], v[212:219], v[62:65]
	v_mfma_f32_16x16x128_f8f6f4 v[58:61], v[10:17], v[212:219], v[58:61]
	v_mfma_f32_16x16x128_f8f6f4 v[46:49], v[2:9], v[220:227], v[46:49]
	v_mfma_f32_16x16x128_f8f6f4 v[42:45], v[10:17], v[220:227], v[42:45]
	s_setprio 0
	s_setprio 1
	v_mfma_f32_16x16x128_f8f6f4 v[86:89], v[18:25], v[196:203], v[86:89]
	v_mfma_f32_16x16x128_f8f6f4 v[82:85], v[26:33], v[196:203], v[82:85]
	v_mfma_f32_16x16x128_f8f6f4 v[70:73], v[18:25], v[204:211], v[70:73]
	v_mfma_f32_16x16x128_f8f6f4 v[66:69], v[26:33], v[204:211], v[66:69]
	v_mfma_f32_16x16x128_f8f6f4 v[54:57], v[18:25], v[212:219], v[54:57]
	v_mfma_f32_16x16x128_f8f6f4 v[50:53], v[26:33], v[212:219], v[50:53]
	v_mfma_f32_16x16x128_f8f6f4 v[38:41], v[18:25], v[220:227], v[38:41]
	v_mfma_f32_16x16x128_f8f6f4 v[34:37], v[26:33], v[220:227], v[34:37]
	s_setprio 2
	s_barrier
	s_add_i32 s76, s76, 2
	s_add_u32 s86, s86, 0x100
	s_addc_u32 s87, s87, 0
	s_add_u32 s74, s74, 0x100
	s_addc_u32 s75, s75, 0
	s_cmp_gt_u32 s76, 29
	s_cbranch_scc0 .LBB0_225
	s_nop 7
	s_nop 7
	s_and_b64 vcc, exec, s[14:15]
	s_cbranch_vccz .LBB0_228
	s_barrier

; #define PG8_STAGE(bufoff, gbase, voff) do { if constexpr (DIAG >= 1) break; _Pragma("unroll") for (int _i = 0; _i < 2; ++_i) \
;         __builtin_amdgcn_global_load_lds((const unsigned*)((const char*)(gbase) + (voff)[_i]), (PG8_LAS unsigned*)(lds + (bufoff) + ldsw + _i * 8192), 16, 0, 0); } while (0)
; #define PG8_LDA(dst, b, h) do { if constexpr (DIAG == 2 || DIAG == 3) break; _Pragma("unroll") for (int m = 0; m < 4; ++m) _Pragma("unroll") for (int k = 0; k < 2; ++k) dst[m][k] = *(const PG8_LAS bf16x8*)(lds + PG8_SA(b, h) + aoff + m * 2048 + k * 1024); } while (0)
; #define PG8_LDB(dst, b, h) do { if constexpr (DIAG == 2 || DIAG == 3) break; _Pragma("unroll") for (int n = 0; n < 2; ++n) _Pragma("unroll") for (int k = 0; k < 2; ++k) dst[n][k] = *(const PG8_LAS bf16x8*)(lds + PG8_SB(b, h) + boff + n * 2048 + k * 1024); } while (0)
; #define PG8_WAIT_V(n) asm volatile("s_waitcnt vmcnt(" #n ")" ::: "memory")
; #define PG8_WAIT_L(n) asm volatile("s_waitcnt lgkmcnt(" #n ")" ::: "memory")
; #define PG8_BAR __builtin_amdgcn_s_barrier()
; #define PG8_LP_ON __builtin_amdgcn_s_setprio(PG8_LOADPRIO)
; #define PG8_LP_OFF __builtin_amdgcn_s_setprio(0)
; #define PG8_LP_ON do {} while (0)
; #define PG8_LP_OFF do {} while (0)
; #define PG8_SCHED __builtin_amdgcn_sched_barrier(0)
;     ...
;             PG8_LP_ON; PG8_LDB(B0, 0, 0); PG8_LDB(B1, 0, 1); PG8_SCHED; PG8_LDA(At, 0, 0); PG8_STAGE(PG8_SA(1, 1), a1 + hstep, voffA);
;             PG8_LP_OFF; PG8_WAIT_V(8); PG8_WAIT_L(0); PG8_BAR; PG8_MMA(0, 0, At, B0); PG8_MMA(0, 1, At, B1); PG8_BAR; PG8_SCHED;
;             PG8_LP_ON; PG8_LDA(At, 0, 1); PG8_STAGE(PG8_SB(0, 0), b2, voffB); PG8_STAGE(PG8_SB(0, 1), b2 + hstep, voffB); PG8_STAGE(PG8_SA(0, 0), a2, voffA);
;             PG8_LP_OFF; PG8_WAIT_V(8); PG8_WAIT_L(0); PG8_BAR; PG8_MMA(1, 0, At, B0); PG8_MMA(1, 1, At, B1); PG8_BAR; PG8_SCHED;
.LBB0_306:
	ds_read_b128 v[26:29], v200
	ds_read_b128 v[30:33], v200 offset:1024
	ds_read_b128 v[18:21], v200 offset:2048
	ds_read_b128 v[22:25], v200 offset:3072
	ds_read_b128 v[10:13], v201
	ds_read_b128 v[14:17], v201 offset:1024
	ds_read_b128 v[2:5], v201 offset:2048
	ds_read_b128 v[6:9], v201 offset:3072
	s_add_u32 s74, s4, 0xffea8080
	s_addc_u32 s75, s5, -1
	s_cmpk_eq_i32 s77, 0x52
	s_cselect_b32 s87, s23, s75
	s_cselect_b32 s86, s22, s74
	s_cselect_b32 s75, s73, s76
	s_cselect_b32 s74, s72, s27
	v_lshl_add_u64 v[196:197], s[4:5], 0, v[172:173]
	s_add_i32 m0, s84, 0xc000
	ds_read_b128 v[180:183], v202
	ds_read_b128 v[184:187], v202 offset:1024
	ds_read_b128 v[188:191], v202 offset:2048
	ds_read_b128 v[192:195], v202 offset:3072
	ds_read_b128 v[204:207], v202 offset:4096
	ds_read_b128 v[208:211], v202 offset:5120
	ds_read_b128 v[212:215], v202 offset:6144
	ds_read_b128 v[216:219], v202 offset:7168
	global_load_lds_dwordx4 v[196:197], off
	v_lshl_add_u64 v[196:197], s[4:5], 0, v[174:175]
	s_add_i32 m0, s84, 0xe000
	s_nop 0
	global_load_lds_dwordx4 v[196:197], off
	s_waitcnt vmcnt(8)
	s_waitcnt lgkmcnt(0)
	s_barrier
	s_setprio 1
	s_waitcnt lgkmcnt(0)
	v_mfma_f32_16x16x128_f8f6f4 v[158:161], v[26:33], v[180:187], v[158:161]
	v_mfma_f32_16x16x128_f8f6f4 v[154:157], v[18:25], v[180:187], v[154:157]
	v_mfma_f32_16x16x128_f8f6f4 v[142:145], v[26:33], v[188:195], v[142:145]
	v_mfma_f32_16x16x128_f8f6f4 v[138:141], v[18:25], v[188:195], v[138:141]
	v_mfma_f32_16x16x128_f8f6f4 v[126:129], v[26:33], v[204:211], v[126:129]
	v_mfma_f32_16x16x128_f8f6f4 v[122:125], v[18:25], v[204:211], v[122:125]
	v_mfma_f32_16x16x128_f8f6f4 v[110:113], v[26:33], v[212:219], v[110:113]
	v_mfma_f32_16x16x128_f8f6f4 v[106:109], v[18:25], v[212:219], v[106:109]
	s_setprio 0
	s_setprio 1
	v_mfma_f32_16x16x128_f8f6f4 v[150:153], v[10:17], v[180:187], v[150:153]
	v_mfma_f32_16x16x128_f8f6f4 v[146:149], v[2:9], v[180:187], v[146:149]
	v_mfma_f32_16x16x128_f8f6f4 v[134:137], v[10:17], v[188:195], v[134:137]
	v_mfma_f32_16x16x128_f8f6f4 v[130:133], v[2:9], v[188:195], v[130:133]
	v_mfma_f32_16x16x128_f8f6f4 v[118:121], v[10:17], v[204:211], v[118:121]
	v_mfma_f32_16x16x128_f8f6f4 v[114:117], v[2:9], v[204:211], v[114:117]
	v_mfma_f32_16x16x128_f8f6f4 v[102:105], v[10:17], v[212:219], v[102:105]
	v_mfma_f32_16x16x128_f8f6f4 v[98:101], v[2:9], v[212:219], v[98:101]
	s_setprio 2
	s_barrier
	s_add_i32 s78, s96, s21
	v_lshl_add_u64 v[180:181], s[74:75], 0, v[166:167]
	s_mov_b32 m0, s78
	ds_read_b128 v[188:191], v202 offset:16384
	ds_read_b128 v[192:195], v202 offset:17408
	ds_read_b128 v[204:207], v202 offset:18432
	ds_read_b128 v[208:211], v202 offset:19456
	ds_read_b128 v[212:215], v202 offset:20480
	ds_read_b128 v[216:219], v202 offset:21504
	ds_read_b128 v[220:223], v202 offset:22528
	ds_read_b128 v[224:227], v202 offset:23552
	global_load_lds_dwordx4 v[180:181], off
	s_add_i32 m0, s78, 0x2000
	s_add_u32 s78, s74, 0x158000
	v_lshl_add_u64 v[182:183], s[74:75], 0, v[168:169]
	s_addc_u32 s79, s75, 0
	s_add_i32 s80, s97, s21
	global_load_lds_dwordx4 v[182:183], off
	v_lshl_add_u64 v[184:185], s[78:79], 0, v[166:167]
	s_mov_b32 m0, s80
	v_lshl_add_u64 v[186:187], s[86:87], 0, v[168:169]
	global_load_lds_dwordx4 v[184:185], off
	v_lshl_add_u64 v[184:185], s[78:79], 0, v[168:169]
	s_add_i32 m0, s80, 0x2000
	s_nop 0
	global_load_lds_dwordx4 v[184:185], off
	v_lshl_add_u64 v[184:185], s[86:87], 0, v[166:167]
	s_mov_b32 m0, s84
	s_nop 0
	global_load_lds_dwordx4 v[184:185], off
	s_mov_b32 m0, s85
	s_nop 0
	global_load_lds_dwordx4 v[186:187], off
	s_waitcnt vmcnt(8)
	s_waitcnt lgkmcnt(0)
	s_barrier
	s_setprio 1
	s_waitcnt lgkmcnt(0)
	v_mfma_f32_16x16x128_f8f6f4 v[94:97], v[26:33], v[188:195], v[94:97]
	v_mfma_f32_16x16x128_f8f6f4 v[90:93], v[18:25], v[188:195], v[90:93]
	v_mfma_f32_16x16x128_f8f6f4 v[78:81], v[26:33], v[204:211], v[78:81]
	v_mfma_f32_16x16x128_f8f6f4 v[74:77], v[18:25], v[204:211], v[74:77]
	v_mfma_f32_16x16x128_f8f6f4 v[62:65], v[26:33], v[212:219], v[62:65]
	v_mfma_f32_16x16x128_f8f6f4 v[58:61], v[18:25], v[212:219], v[58:61]
	v_mfma_f32_16x16x128_f8f6f4 v[46:49], v[26:33], v[220:227], v[46:49]
	v_mfma_f32_16x16x128_f8f6f4 v[42:45], v[18:25], v[220:227], v[42:45]
	s_setprio 0
	s_setprio 1
	v_mfma_f32_16x16x128_f8f6f4 v[86:89], v[10:17], v[188:195], v[86:89]
	v_mfma_f32_16x16x128_f8f6f4 v[82:85], v[2:9], v[188:195], v[82:85]
	v_mfma_f32_16x16x128_f8f6f4 v[70:73], v[10:17], v[204:211], v[70:73]
	v_mfma_f32_16x16x128_f8f6f4 v[66:69], v[2:9], v[204:211], v[66:69]
	v_mfma_f32_16x16x128_f8f6f4 v[54:57], v[10:17], v[212:219], v[54:57]
	v_mfma_f32_16x16x128_f8f6f4 v[50:53], v[2:9], v[212:219], v[50:53]
	v_mfma_f32_16x16x128_f8f6f4 v[38:41], v[10:17], v[220:227], v[38:41]
	v_mfma_f32_16x16x128_f8f6f4 v[34:37], v[2:9], v[220:227], v[34:37]
	s_setprio 2
	s_barrier
; #define PG8_STAGE(bufoff, gbase, voff) do { if constexpr (DIAG >= 1) break; _Pragma("unroll") for (int _i = 0; _i < 2; ++_i) \
;         __builtin_amdgcn_global_load_lds((const unsigned*)((const char*)(gbase) + (voff)[_i]), (PG8_LAS unsigned*)(lds + (bufoff) + ldsw + _i * 8192), 16, 0, 0); } while (0)
; #define PG8_LDA(dst, b, h) do { if constexpr (DIAG == 2 || DIAG == 3) break; _Pragma("unroll") for (int m = 0; m < 4; ++m) _Pragma("unroll") for (int k = 0; k < 2; ++k) dst[m][k] = *(const PG8_LAS bf16x8*)(lds + PG8_SA(b, h) + aoff + m * 2048 + k * 1024); } while (0)
; #define PG8_LDB(dst, b, h) do { if constexpr (DIAG == 2 || DIAG == 3) break; _Pragma("unroll") for (int n = 0; n < 2; ++n) _Pragma("unroll") for (int k = 0; k < 2; ++k) dst[n][k] = *(const PG8_LAS bf16x8*)(lds + PG8_SB(b, h) + boff + n * 2048 + k * 1024); } while (0)
; #define PG8_WAIT_V(n) asm volatile("s_waitcnt vmcnt(" #n ")" ::: "memory")
; #define PG8_WAIT_L(n) asm volatile("s_waitcnt lgkmcnt(" #n ")" ::: "memory")
; #define PG8_BAR __builtin_amdgcn_s_barrier()
; #define PG8_LP_ON __builtin_amdgcn_s_setprio(PG8_LOADPRIO)
; #define PG8_LP_OFF __builtin_amdgcn_s_setprio(0)
; #define PG8_LP_ON do {} while (0)
; #define PG8_LP_OFF do {} while (0)
; #define PG8_SCHED __builtin_amdgcn_sched_barrier(0)
;     ...
;             PG8_LP_ON; PG8_LDB(B0, 1, 0); PG8_LDB(B1, 1, 1); PG8_SCHED; PG8_LDA(At, 1, 0); PG8_STAGE(PG8_SA(0, 1), a2 + hstep, voffA);
;             PG8_LP_OFF; PG8_WAIT_V(8); PG8_WAIT_L(0); PG8_BAR; PG8_MMA(0, 0, At, B0); PG8_MMA(0, 1, At, B1); PG8_BAR; PG8_SCHED;
;             PG8_LP_ON; PG8_LDA(At, 1, 1); PG8_STAGE(PG8_SB(1, 0), b3, voffB); PG8_STAGE(PG8_SB(1, 1), b3 + hstep, voffB); PG8_STAGE(PG8_SA(1, 0), a3, voffA);
;             PG8_LP_OFF; PG8_WAIT_V(8); PG8_WAIT_L(0); PG8_BAR; PG8_MMA(1, 0, At, B0); PG8_MMA(1, 1, At, B1); PG8_BAR; PG8_SCHED;
	s_add_i32 s80, 0, 0x18000
	s_add_i32 s81, 0, 0x1c000
	v_add_u32_e32 v14, s80, v198
	v_add_u32_e32 v30, s81, v198
	ds_read_b128 v[2:5], v14
	ds_read_b128 v[6:9], v14 offset:1024
	ds_read_b128 v[10:13], v14 offset:2048
	ds_read_b128 v[14:17], v14 offset:3072
	ds_read_b128 v[18:21], v30
	ds_read_b128 v[22:25], v30 offset:1024
	ds_read_b128 v[26:29], v30 offset:2048
	ds_read_b128 v[30:33], v30 offset:3072
	s_add_u32 s78, s86, 0x158000
	s_addc_u32 s79, s87, 0
	s_mov_b32 m0, s88
	v_lshl_add_u64 v[196:197], s[78:79], 0, v[166:167]
	ds_read_b128 v[188:191], v202 offset:32768
	ds_read_b128 v[192:195], v202 offset:33792
	ds_read_b128 v[204:207], v202 offset:34816
	ds_read_b128 v[208:211], v202 offset:35840
	ds_read_b128 v[212:215], v202 offset:36864
	ds_read_b128 v[216:219], v202 offset:37888
	ds_read_b128 v[220:223], v202 offset:38912
	ds_read_b128 v[224:227], v202 offset:39936
	global_load_lds_dwordx4 v[196:197], off
	v_lshl_add_u64 v[196:197], s[78:79], 0, v[168:169]
	s_mov_b32 m0, s89
	s_nop 0
	global_load_lds_dwordx4 v[196:197], off
	s_waitcnt vmcnt(8)
	s_waitcnt lgkmcnt(0)
	s_barrier
	s_setprio 1
	s_waitcnt lgkmcnt(0)
	v_mfma_f32_16x16x128_f8f6f4 v[158:161], v[2:9], v[188:195], v[158:161]
	v_mfma_f32_16x16x128_f8f6f4 v[154:157], v[10:17], v[188:195], v[154:157]
	v_mfma_f32_16x16x128_f8f6f4 v[142:145], v[2:9], v[204:211], v[142:145]
	v_mfma_f32_16x16x128_f8f6f4 v[138:141], v[10:17], v[204:211], v[138:141]
	v_mfma_f32_16x16x128_f8f6f4 v[126:129], v[2:9], v[212:219], v[126:129]
	v_mfma_f32_16x16x128_f8f6f4 v[122:125], v[10:17], v[212:219], v[122:125]
	v_mfma_f32_16x16x128_f8f6f4 v[110:113], v[2:9], v[220:227], v[110:113]
	v_mfma_f32_16x16x128_f8f6f4 v[106:109], v[10:17], v[220:227], v[106:109]
	s_setprio 0
	s_setprio 1
	v_mfma_f32_16x16x128_f8f6f4 v[150:153], v[18:25], v[188:195], v[150:153]
	v_mfma_f32_16x16x128_f8f6f4 v[146:149], v[26:33], v[188:195], v[146:149]
	v_mfma_f32_16x16x128_f8f6f4 v[134:137], v[18:25], v[204:211], v[134:137]
	v_mfma_f32_16x16x128_f8f6f4 v[130:133], v[26:33], v[204:211], v[130:133]
	v_mfma_f32_16x16x128_f8f6f4 v[118:121], v[18:25], v[212:219], v[118:121]
	v_mfma_f32_16x16x128_f8f6f4 v[114:117], v[26:33], v[212:219], v[114:117]
	v_mfma_f32_16x16x128_f8f6f4 v[102:105], v[18:25], v[220:227], v[102:105]
	v_mfma_f32_16x16x128_f8f6f4 v[98:101], v[26:33], v[220:227], v[98:101]
	s_setprio 2
	s_barrier
	s_add_i32 s78, s80, s21
	v_lshl_add_u64 v[180:181], v[180:181], 0, s[14:15]
	s_mov_b32 m0, s78
	ds_read_b128 v[188:191], v202 offset:49152
	ds_read_b128 v[192:195], v202 offset:50176
	ds_read_b128 v[204:207], v202 offset:51200
	ds_read_b128 v[208:211], v202 offset:52224
	ds_read_b128 v[212:215], v202 offset:53248
	ds_read_b128 v[216:219], v202 offset:54272
	ds_read_b128 v[220:223], v202 offset:55296
	ds_read_b128 v[224:227], v202 offset:56320
	global_load_lds_dwordx4 v[180:181], off
	s_add_i32 m0, s78, 0x2000
	s_add_u32 s74, s74, 0x158080
	v_lshl_add_u64 v[180:181], v[182:183], 0, s[14:15]
	s_addc_u32 s75, s75, 0
	s_add_i32 s78, s81, s21
	global_load_lds_dwordx4 v[180:181], off
	v_lshl_add_u64 v[180:181], s[74:75], 0, v[166:167]
	s_mov_b32 m0, s78
	s_nop 0
	global_load_lds_dwordx4 v[180:181], off
	v_lshl_add_u64 v[180:181], s[74:75], 0, v[168:169]
	s_add_i32 m0, s78, 0x2000
	s_nop 0
	global_load_lds_dwordx4 v[180:181], off
	v_lshl_add_u64 v[180:181], v[184:185], 0, s[14:15]
	s_mov_b32 m0, s94
	s_nop 0
	global_load_lds_dwordx4 v[180:181], off
	v_lshl_add_u64 v[180:181], v[186:187], 0, s[14:15]
	s_mov_b32 m0, s95
	s_nop 0
	global_load_lds_dwordx4 v[180:181], off
	s_waitcnt vmcnt(8)
	s_waitcnt lgkmcnt(0)
	s_barrier
	s_setprio 1
	s_waitcnt lgkmcnt(0)
	v_mfma_f32_16x16x128_f8f6f4 v[94:97], v[2:9], v[188:195], v[94:97]
	v_mfma_f32_16x16x128_f8f6f4 v[90:93], v[10:17], v[188:195], v[90:93]
	v_mfma_f32_16x16x128_f8f6f4 v[78:81], v[2:9], v[204:211], v[78:81]
	v_mfma_f32_16x16x128_f8f6f4 v[74:77], v[10:17], v[204:211], v[74:77]
	v_mfma_f32_16x16x128_f8f6f4 v[62:65], v[2:9], v[212:219], v[62:65]
	v_mfma_f32_16x16x128_f8f6f4 v[58:61], v[10:17], v[212:219], v[58:61]
	v_mfma_f32_16x16x128_f8f6f4 v[46:49], v[2:9], v[220:227], v[46:49]
	v_mfma_f32_16x16x128_f8f6f4 v[42:45], v[10:17], v[220:227], v[42:45]
	s_setprio 0
	s_setprio 1
	v_mfma_f32_16x16x128_f8f6f4 v[86:89], v[18:25], v[188:195], v[86:89]
	v_mfma_f32_16x16x128_f8f6f4 v[82:85], v[26:33], v[188:195], v[82:85]
	v_mfma_f32_16x16x128_f8f6f4 v[70:73], v[18:25], v[204:211], v[70:73]
	v_mfma_f32_16x16x128_f8f6f4 v[66:69], v[26:33], v[204:211], v[66:69]
	v_mfma_f32_16x16x128_f8f6f4 v[54:57], v[18:25], v[212:219], v[54:57]
	v_mfma_f32_16x16x128_f8f6f4 v[50:53], v[26:33], v[212:219], v[50:53]
	v_mfma_f32_16x16x128_f8f6f4 v[38:41], v[18:25], v[220:227], v[38:41]
	v_mfma_f32_16x16x128_f8f6f4 v[34:37], v[26:33], v[220:227], v[34:37]
	s_setprio 2
	s_barrier
	s_add_i32 s77, s77, 2
	s_add_u32 s4, s4, 0x100
	s_addc_u32 s5, s5, 0
	s_add_u32 s27, s27, 0x100
	s_addc_u32 s76, s76, 0
	s_cmpk_gt_u32 s77, 0x53
	s_cbranch_scc0 .LBB0_306
	s_nop 7
	s_nop 7
	s_and_b64 vcc, exec, s[16:17]
	s_cbranch_vccz .LBB0_309
	s_barrier

; #define PG8_STAGE(bufoff, gbase, voff) do { if constexpr (DIAG >= 1) break; _Pragma("unroll") for (int _i = 0; _i < 2; ++_i) \
;         __builtin_amdgcn_global_load_lds((const unsigned*)((const char*)(gbase) + (voff)[_i]), (PG8_LAS unsigned*)(lds + (bufoff) + ldsw + _i * 8192), 16, 0, 0); } while (0)
; #define PG8_LDA(dst, b, h) do { if constexpr (DIAG == 2 || DIAG == 3) break; _Pragma("unroll") for (int m = 0; m < 4; ++m) _Pragma("unroll") for (int k = 0; k < 2; ++k) dst[m][k] = *(const PG8_LAS bf16x8*)(lds + PG8_SA(b, h) + aoff + m * 2048 + k * 1024); } while (0)
; #define PG8_LDB(dst, b, h) do { if constexpr (DIAG == 2 || DIAG == 3) break; _Pragma("unroll") for (int n = 0; n < 2; ++n) _Pragma("unroll") for (int k = 0; k < 2; ++k) dst[n][k] = *(const PG8_LAS bf16x8*)(lds + PG8_SB(b, h) + boff + n * 2048 + k * 1024); } while (0)
; #define PG8_WAIT_V(n) asm volatile("s_waitcnt vmcnt(" #n ")" ::: "memory")
; #define PG8_WAIT_L(n) asm volatile("s_waitcnt lgkmcnt(" #n ")" ::: "memory")
; #define PG8_BAR __builtin_amdgcn_s_barrier()
; #define PG8_LP_ON __builtin_amdgcn_s_setprio(PG8_LOADPRIO)
; #define PG8_LP_OFF __builtin_amdgcn_s_setprio(0)
; #define PG8_LP_ON do {} while (0)
; #define PG8_LP_OFF do {} while (0)
; #define PG8_SCHED __builtin_amdgcn_sched_barrier(0)
;     ...
;             PG8_LP_ON; PG8_LDB(B0, 0, 0); PG8_LDB(B1, 0, 1); PG8_SCHED; PG8_LDA(At, 0, 0); PG8_STAGE(PG8_SA(1, 1), a1 + hstep, voffA);
;             PG8_LP_OFF; PG8_WAIT_V(8); PG8_WAIT_L(0); PG8_BAR; PG8_MMA(0, 0, At, B0); PG8_MMA(0, 1, At, B1); PG8_BAR; PG8_SCHED;
;             PG8_LP_ON; PG8_LDA(At, 0, 1); PG8_STAGE(PG8_SB(0, 0), b2, voffB); PG8_STAGE(PG8_SB(0, 1), b2 + hstep, voffB); PG8_STAGE(PG8_SA(0, 0), a2, voffA);
;             PG8_LP_OFF; PG8_WAIT_V(8); PG8_WAIT_L(0); PG8_BAR; PG8_MMA(1, 0, At, B0); PG8_MMA(1, 1, At, B1); PG8_BAR; PG8_SCHED;
.LBB0_505:
	ds_read_b128 v[26:29], v205
	ds_read_b128 v[30:33], v205 offset:1024
	ds_read_b128 v[18:21], v205 offset:2048
	ds_read_b128 v[22:25], v205 offset:3072
	ds_read_b128 v[10:13], v206
	ds_read_b128 v[14:17], v206 offset:1024
	ds_read_b128 v[2:5], v206 offset:2048
	ds_read_b128 v[6:9], v206 offset:3072
	s_add_u32 s76, s74, 0xfff80080
	s_addc_u32 s77, s75, -1
	s_cmp_eq_u32 s82, 28
	s_cselect_b32 s79, s19, s77
	s_cselect_b32 s78, s95, s76
	s_cselect_b32 s77, s17, s81
	s_cselect_b32 s76, s96, s80
	v_lshl_add_u64 v[232:233], s[74:75], 0, v[174:175]
	s_add_i32 m0, s55, 0xc000
	ds_read_b128 v[182:185], v207
	ds_read_b128 v[186:189], v207 offset:1024
	ds_read_b128 v[208:211], v207 offset:2048
	ds_read_b128 v[212:215], v207 offset:3072
	ds_read_b128 v[216:219], v207 offset:4096
	ds_read_b128 v[220:223], v207 offset:5120
	ds_read_b128 v[224:227], v207 offset:6144
	ds_read_b128 v[228:231], v207 offset:7168
	global_load_lds_dwordx4 v[232:233], off
	v_lshl_add_u64 v[232:233], s[74:75], 0, v[176:177]
	s_add_i32 m0, s55, 0xe000
	s_nop 0
	global_load_lds_dwordx4 v[232:233], off
	s_waitcnt vmcnt(8)
	s_waitcnt lgkmcnt(0)
	s_barrier
	s_setprio 1
	s_waitcnt lgkmcnt(0)
	v_mfma_f32_16x16x128_f8f6f4 v[158:161], v[26:33], v[182:189], v[158:161]
	v_mfma_f32_16x16x128_f8f6f4 v[154:157], v[18:25], v[182:189], v[154:157]
	v_mfma_f32_16x16x128_f8f6f4 v[146:149], v[26:33], v[208:215], v[146:149]
	v_mfma_f32_16x16x128_f8f6f4 v[138:141], v[18:25], v[208:215], v[138:141]
	v_mfma_f32_16x16x128_f8f6f4 v[130:133], v[26:33], v[216:223], v[130:133]
	v_mfma_f32_16x16x128_f8f6f4 v[122:125], v[18:25], v[216:223], v[122:125]
	v_mfma_f32_16x16x128_f8f6f4 v[114:117], v[26:33], v[224:231], v[114:117]
	v_mfma_f32_16x16x128_f8f6f4 v[106:109], v[18:25], v[224:231], v[106:109]
	s_setprio 0
	s_setprio 1
	v_mfma_f32_16x16x128_f8f6f4 v[150:153], v[10:17], v[182:189], v[150:153]
	v_mfma_f32_16x16x128_f8f6f4 v[142:145], v[2:9], v[182:189], v[142:145]
	v_mfma_f32_16x16x128_f8f6f4 v[134:137], v[10:17], v[208:215], v[134:137]
	v_mfma_f32_16x16x128_f8f6f4 v[126:129], v[2:9], v[208:215], v[126:129]
	v_mfma_f32_16x16x128_f8f6f4 v[118:121], v[10:17], v[216:223], v[118:121]
	v_mfma_f32_16x16x128_f8f6f4 v[110:113], v[2:9], v[216:223], v[110:113]
	v_mfma_f32_16x16x128_f8f6f4 v[102:105], v[10:17], v[224:231], v[102:105]
	v_mfma_f32_16x16x128_f8f6f4 v[98:101], v[2:9], v[224:231], v[98:101]
	s_setprio 2
	s_barrier
	s_add_i32 s83, s92, s86
	v_lshl_add_u64 v[182:183], s[76:77], 0, v[168:169]
	s_mov_b32 m0, s83
	ds_read_b128 v[208:211], v207 offset:16384
	ds_read_b128 v[212:215], v207 offset:17408
	ds_read_b128 v[216:219], v207 offset:18432
	ds_read_b128 v[220:223], v207 offset:19456
	ds_read_b128 v[224:227], v207 offset:20480
	ds_read_b128 v[228:231], v207 offset:21504
	ds_read_b128 v[232:235], v207 offset:22528
	ds_read_b128 v[236:239], v207 offset:23552
	global_load_lds_dwordx4 v[182:183], off
	s_add_i32 m0, s83, 0x2000
	s_add_u32 vcc_lo, s76, 0x80000
	v_lshl_add_u64 v[184:185], s[76:77], 0, v[172:173]
	s_addc_u32 vcc_hi, s77, 0
	s_add_i32 s83, s93, s86
	global_load_lds_dwordx4 v[184:185], off
	v_lshl_add_u64 v[186:187], vcc, 0, v[168:169]
	s_mov_b32 m0, s83
	v_lshl_add_u64 v[188:189], s[78:79], 0, v[170:171]
	global_load_lds_dwordx4 v[186:187], off
	v_lshl_add_u64 v[186:187], vcc, 0, v[172:173]
	s_add_i32 m0, s83, 0x2000
	s_nop 0
	global_load_lds_dwordx4 v[186:187], off
	v_lshl_add_u64 v[186:187], s[78:79], 0, v[166:167]
	s_mov_b32 m0, s55
	s_nop 0
	global_load_lds_dwordx4 v[186:187], off
	s_mov_b32 m0, s73
	s_nop 0
	global_load_lds_dwordx4 v[188:189], off
	s_waitcnt vmcnt(8)
	s_waitcnt lgkmcnt(0)
	s_barrier
	s_setprio 1
	s_waitcnt lgkmcnt(0)
	v_mfma_f32_16x16x128_f8f6f4 v[94:97], v[26:33], v[208:215], v[94:97]
	v_mfma_f32_16x16x128_f8f6f4 v[90:93], v[18:25], v[208:215], v[90:93]
	v_mfma_f32_16x16x128_f8f6f4 v[82:85], v[26:33], v[216:223], v[82:85]
	v_mfma_f32_16x16x128_f8f6f4 v[74:77], v[18:25], v[216:223], v[74:77]
	v_mfma_f32_16x16x128_f8f6f4 v[66:69], v[26:33], v[224:231], v[66:69]
	v_mfma_f32_16x16x128_f8f6f4 v[58:61], v[18:25], v[224:231], v[58:61]
	v_mfma_f32_16x16x128_f8f6f4 v[50:53], v[26:33], v[232:239], v[50:53]
	v_mfma_f32_16x16x128_f8f6f4 v[42:45], v[18:25], v[232:239], v[42:45]
	s_setprio 0
	s_setprio 1
	v_mfma_f32_16x16x128_f8f6f4 v[86:89], v[10:17], v[208:215], v[86:89]
	v_mfma_f32_16x16x128_f8f6f4 v[78:81], v[2:9], v[208:215], v[78:81]
	v_mfma_f32_16x16x128_f8f6f4 v[70:73], v[10:17], v[216:223], v[70:73]
	v_mfma_f32_16x16x128_f8f6f4 v[62:65], v[2:9], v[216:223], v[62:65]
	v_mfma_f32_16x16x128_f8f6f4 v[54:57], v[10:17], v[224:231], v[54:57]
	v_mfma_f32_16x16x128_f8f6f4 v[46:49], v[2:9], v[224:231], v[46:49]
	v_mfma_f32_16x16x128_f8f6f4 v[38:41], v[10:17], v[232:239], v[38:41]
	v_mfma_f32_16x16x128_f8f6f4 v[34:37], v[2:9], v[232:239], v[34:37]
	s_setprio 2
	s_barrier
; #define PG8_STAGE(bufoff, gbase, voff) do { if constexpr (DIAG >= 1) break; _Pragma("unroll") for (int _i = 0; _i < 2; ++_i) \
;         __builtin_amdgcn_global_load_lds((const unsigned*)((const char*)(gbase) + (voff)[_i]), (PG8_LAS unsigned*)(lds + (bufoff) + ldsw + _i * 8192), 16, 0, 0); } while (0)
; #define PG8_LDA(dst, b, h) do { if constexpr (DIAG == 2 || DIAG == 3) break; _Pragma("unroll") for (int m = 0; m < 4; ++m) _Pragma("unroll") for (int k = 0; k < 2; ++k) dst[m][k] = *(const PG8_LAS bf16x8*)(lds + PG8_SA(b, h) + aoff + m * 2048 + k * 1024); } while (0)
; #define PG8_LDB(dst, b, h) do { if constexpr (DIAG == 2 || DIAG == 3) break; _Pragma("unroll") for (int n = 0; n < 2; ++n) _Pragma("unroll") for (int k = 0; k < 2; ++k) dst[n][k] = *(const PG8_LAS bf16x8*)(lds + PG8_SB(b, h) + boff + n * 2048 + k * 1024); } while (0)
; #define PG8_WAIT_V(n) asm volatile("s_waitcnt vmcnt(" #n ")" ::: "memory")
; #define PG8_WAIT_L(n) asm volatile("s_waitcnt lgkmcnt(" #n ")" ::: "memory")
; #define PG8_BAR __builtin_amdgcn_s_barrier()
; #define PG8_LP_ON __builtin_amdgcn_s_setprio(PG8_LOADPRIO)
; #define PG8_LP_OFF __builtin_amdgcn_s_setprio(0)
; #define PG8_LP_ON do {} while (0)
; #define PG8_LP_OFF do {} while (0)
; #define PG8_SCHED __builtin_amdgcn_sched_barrier(0)
;     ...
;             PG8_LP_ON; PG8_LDB(B0, 1, 0); PG8_LDB(B1, 1, 1); PG8_SCHED; PG8_LDA(At, 1, 0); PG8_STAGE(PG8_SA(0, 1), a2 + hstep, voffA);
;             PG8_LP_OFF; PG8_WAIT_V(8); PG8_WAIT_L(0); PG8_BAR; PG8_MMA(0, 0, At, B0); PG8_MMA(0, 1, At, B1); PG8_BAR; PG8_SCHED;
;             PG8_LP_ON; PG8_LDA(At, 1, 1); PG8_STAGE(PG8_SB(1, 0), b3, voffB); PG8_STAGE(PG8_SB(1, 1), b3 + hstep, voffB); PG8_STAGE(PG8_SA(1, 0), a3, voffA);
;             PG8_LP_OFF; PG8_WAIT_V(8); PG8_WAIT_L(0); PG8_BAR; PG8_MMA(1, 0, At, B0); PG8_MMA(1, 1, At, B1); PG8_BAR; PG8_SCHED;
	s_add_i32 s83, 0, 0x18000
	s_add_i32 s97, 0, 0x1c000
	v_add_u32_e32 v14, s83, v203
	v_add_u32_e32 v30, s97, v203
	ds_read_b128 v[2:5], v14
	ds_read_b128 v[6:9], v14 offset:1024
	ds_read_b128 v[10:13], v14 offset:2048
	ds_read_b128 v[14:17], v14 offset:3072
	ds_read_b128 v[18:21], v30
	ds_read_b128 v[22:25], v30 offset:1024
	ds_read_b128 v[26:29], v30 offset:2048
	ds_read_b128 v[30:33], v30 offset:3072
	s_add_u32 s78, s78, 0x80000
	s_addc_u32 s79, s79, 0
	s_mov_b32 m0, s87
	v_lshl_add_u64 v[240:241], s[78:79], 0, v[166:167]
	ds_read_b128 v[208:211], v207 offset:32768
	ds_read_b128 v[212:215], v207 offset:33792
	ds_read_b128 v[216:219], v207 offset:34816
	ds_read_b128 v[220:223], v207 offset:35840
	ds_read_b128 v[224:227], v207 offset:36864
	ds_read_b128 v[228:231], v207 offset:37888
	ds_read_b128 v[232:235], v207 offset:38912
	ds_read_b128 v[236:239], v207 offset:39936
	global_load_lds_dwordx4 v[240:241], off
	v_lshl_add_u64 v[240:241], s[78:79], 0, v[170:171]
	s_mov_b32 m0, s88
	s_nop 0
	global_load_lds_dwordx4 v[240:241], off
	s_waitcnt vmcnt(8)
	s_waitcnt lgkmcnt(0)
	s_barrier
	s_setprio 1
	s_waitcnt lgkmcnt(0)
	v_mfma_f32_16x16x128_f8f6f4 v[158:161], v[2:9], v[208:215], v[158:161]
	v_mfma_f32_16x16x128_f8f6f4 v[154:157], v[10:17], v[208:215], v[154:157]
	v_mfma_f32_16x16x128_f8f6f4 v[146:149], v[2:9], v[216:223], v[146:149]
	v_mfma_f32_16x16x128_f8f6f4 v[138:141], v[10:17], v[216:223], v[138:141]
	v_mfma_f32_16x16x128_f8f6f4 v[130:133], v[2:9], v[224:231], v[130:133]
	v_mfma_f32_16x16x128_f8f6f4 v[122:125], v[10:17], v[224:231], v[122:125]
	v_mfma_f32_16x16x128_f8f6f4 v[114:117], v[2:9], v[232:239], v[114:117]
	v_mfma_f32_16x16x128_f8f6f4 v[106:109], v[10:17], v[232:239], v[106:109]
	s_setprio 0
	s_setprio 1
	v_mfma_f32_16x16x128_f8f6f4 v[150:153], v[18:25], v[208:215], v[150:153]
	v_mfma_f32_16x16x128_f8f6f4 v[142:145], v[26:33], v[208:215], v[142:145]
	v_mfma_f32_16x16x128_f8f6f4 v[134:137], v[18:25], v[216:223], v[134:137]
	v_mfma_f32_16x16x128_f8f6f4 v[126:129], v[26:33], v[216:223], v[126:129]
	v_mfma_f32_16x16x128_f8f6f4 v[118:121], v[18:25], v[224:231], v[118:121]
	v_mfma_f32_16x16x128_f8f6f4 v[110:113], v[26:33], v[224:231], v[110:113]
	v_mfma_f32_16x16x128_f8f6f4 v[102:105], v[18:25], v[232:239], v[102:105]
	v_mfma_f32_16x16x128_f8f6f4 v[98:101], v[26:33], v[232:239], v[98:101]
	s_setprio 2
	s_barrier
	s_add_i32 s78, s83, s86
	v_lshl_add_u64 v[182:183], v[182:183], 0, s[10:11]
	s_mov_b32 m0, s78
	ds_read_b128 v[208:211], v207 offset:49152
	ds_read_b128 v[212:215], v207 offset:50176
	ds_read_b128 v[216:219], v207 offset:51200
	ds_read_b128 v[220:223], v207 offset:52224
	ds_read_b128 v[224:227], v207 offset:53248
	ds_read_b128 v[228:231], v207 offset:54272
	ds_read_b128 v[232:235], v207 offset:55296
	ds_read_b128 v[236:239], v207 offset:56320
	global_load_lds_dwordx4 v[182:183], off
	s_add_i32 m0, s78, 0x2000
	s_add_u32 s76, s76, 0x80080
	v_lshl_add_u64 v[182:183], v[184:185], 0, s[10:11]
	s_addc_u32 s77, s77, 0
	s_add_i32 s78, s97, s86
	global_load_lds_dwordx4 v[182:183], off
	v_lshl_add_u64 v[182:183], s[76:77], 0, v[168:169]
	s_mov_b32 m0, s78
	s_nop 0
	global_load_lds_dwordx4 v[182:183], off
	v_lshl_add_u64 v[182:183], s[76:77], 0, v[172:173]
	s_add_i32 m0, s78, 0x2000
	s_nop 0
	global_load_lds_dwordx4 v[182:183], off
	v_lshl_add_u64 v[182:183], v[186:187], 0, s[10:11]
	s_mov_b32 m0, s89
	s_nop 0
	global_load_lds_dwordx4 v[182:183], off
	v_lshl_add_u64 v[182:183], v[188:189], 0, s[10:11]
	s_mov_b32 m0, s90
	s_nop 0
	global_load_lds_dwordx4 v[182:183], off
	s_waitcnt vmcnt(8)
	s_waitcnt lgkmcnt(0)
	s_barrier
	s_setprio 1
	s_waitcnt lgkmcnt(0)
	v_mfma_f32_16x16x128_f8f6f4 v[94:97], v[2:9], v[208:215], v[94:97]
	v_mfma_f32_16x16x128_f8f6f4 v[90:93], v[10:17], v[208:215], v[90:93]
	v_mfma_f32_16x16x128_f8f6f4 v[82:85], v[2:9], v[216:223], v[82:85]
	v_mfma_f32_16x16x128_f8f6f4 v[74:77], v[10:17], v[216:223], v[74:77]
	v_mfma_f32_16x16x128_f8f6f4 v[66:69], v[2:9], v[224:231], v[66:69]
	v_mfma_f32_16x16x128_f8f6f4 v[58:61], v[10:17], v[224:231], v[58:61]
	v_mfma_f32_16x16x128_f8f6f4 v[50:53], v[2:9], v[232:239], v[50:53]
	v_mfma_f32_16x16x128_f8f6f4 v[42:45], v[10:17], v[232:239], v[42:45]
	s_setprio 0
	s_setprio 1
	v_mfma_f32_16x16x128_f8f6f4 v[86:89], v[18:25], v[208:215], v[86:89]
	v_mfma_f32_16x16x128_f8f6f4 v[78:81], v[26:33], v[208:215], v[78:81]
	v_mfma_f32_16x16x128_f8f6f4 v[70:73], v[18:25], v[216:223], v[70:73]
	v_mfma_f32_16x16x128_f8f6f4 v[62:65], v[26:33], v[216:223], v[62:65]
	v_mfma_f32_16x16x128_f8f6f4 v[54:57], v[18:25], v[224:231], v[54:57]
	v_mfma_f32_16x16x128_f8f6f4 v[46:49], v[26:33], v[224:231], v[46:49]
	v_mfma_f32_16x16x128_f8f6f4 v[38:41], v[18:25], v[232:239], v[38:41]
	v_mfma_f32_16x16x128_f8f6f4 v[34:37], v[26:33], v[232:239], v[34:37]
	s_setprio 2
	s_barrier
	s_add_i32 s82, s82, 2
	s_add_u32 s74, s74, 0x100
	s_addc_u32 s75, s75, 0
	s_add_u32 s80, s80, 0x100
	s_addc_u32 s81, s81, 0
	s_cmp_gt_u32 s82, 29
	s_cbranch_scc0 .LBB0_505
	s_nop 7
	s_nop 7
	s_and_b64 vcc, exec, s[12:13]
	s_cbranch_vccz .LBB0_508
	s_barrier

; #define PG8_STAGE(bufoff, gbase, voff) do { if constexpr (DIAG >= 1) break; _Pragma("unroll") for (int _i = 0; _i < 2; ++_i) \
;         __builtin_amdgcn_global_load_lds((const unsigned*)((const char*)(gbase) + (voff)[_i]), (PG8_LAS unsigned*)(lds + (bufoff) + ldsw + _i * 8192), 16, 0, 0); } while (0)
; #define PG8_LDA(dst, b, h) do { if constexpr (DIAG == 2 || DIAG == 3) break; _Pragma("unroll") for (int m = 0; m < 4; ++m) _Pragma("unroll") for (int k = 0; k < 2; ++k) dst[m][k] = *(const PG8_LAS bf16x8*)(lds + PG8_SA(b, h) + aoff + m * 2048 + k * 1024); } while (0)
; #define PG8_LDB(dst, b, h) do { if constexpr (DIAG == 2 || DIAG == 3) break; _Pragma("unroll") for (int n = 0; n < 2; ++n) _Pragma("unroll") for (int k = 0; k < 2; ++k) dst[n][k] = *(const PG8_LAS bf16x8*)(lds + PG8_SB(b, h) + boff + n * 2048 + k * 1024); } while (0)
; #define PG8_WAIT_V(n) asm volatile("s_waitcnt vmcnt(" #n ")" ::: "memory")
; #define PG8_WAIT_L(n) asm volatile("s_waitcnt lgkmcnt(" #n ")" ::: "memory")
; #define PG8_BAR __builtin_amdgcn_s_barrier()
; #define PG8_LP_ON __builtin_amdgcn_s_setprio(PG8_LOADPRIO)
; #define PG8_LP_OFF __builtin_amdgcn_s_setprio(0)
; #define PG8_LP_ON do {} while (0)
; #define PG8_LP_OFF do {} while (0)
; #define PG8_SCHED __builtin_amdgcn_sched_barrier(0)
;     ...
;             PG8_LP_ON; PG8_LDB(B0, 0, 0); PG8_LDB(B1, 0, 1); PG8_SCHED; PG8_LDA(At, 0, 0); PG8_STAGE(PG8_SA(1, 1), a1 + hstep, voffA);
;             PG8_LP_OFF; PG8_WAIT_V(8); PG8_WAIT_L(0); PG8_BAR; PG8_MMA(0, 0, At, B0); PG8_MMA(0, 1, At, B1); PG8_BAR; PG8_SCHED;
;             PG8_LP_ON; PG8_LDA(At, 0, 1); PG8_STAGE(PG8_SB(0, 0), b2, voffB); PG8_STAGE(PG8_SB(0, 1), b2 + hstep, voffB); PG8_STAGE(PG8_SA(0, 0), a2, voffA);
;             PG8_LP_OFF; PG8_WAIT_V(8); PG8_WAIT_L(0); PG8_BAR; PG8_MMA(1, 0, At, B0); PG8_MMA(1, 1, At, B1); PG8_BAR; PG8_SCHED;
.LBB0_521:
	ds_read_b128 v[146:149], v153
	ds_read_b128 v[156:159], v153 offset:1024
	ds_read_b128 v[166:169], v153 offset:2048
	ds_read_b128 v[170:173], v153 offset:3072
	ds_read_b128 v[174:177], v154
	ds_read_b128 v[178:181], v154 offset:1024
	ds_read_b128 v[182:185], v154 offset:2048
	ds_read_b128 v[186:189], v154 offset:3072
	s_add_u32 s74, s72, 0xfff00080
	s_addc_u32 s75, s73, -1
	s_cmp_eq_u32 s91, 60
	s_cselect_b32 s77, s17, s75
	s_cselect_b32 s76, s80, s74
	s_cselect_b32 s75, s15, s83
	s_cselect_b32 s74, s81, s82
	v_lshl_add_u64 v[160:161], s[72:73], 0, v[138:139]
	s_add_i32 m0, s23, 0xc000
	ds_read_b128 v[192:195], v155
	ds_read_b128 v[196:199], v155 offset:1024
	ds_read_b128 v[200:203], v155 offset:2048
	ds_read_b128 v[204:207], v155 offset:3072
	ds_read_b128 v[208:211], v155 offset:4096
	ds_read_b128 v[212:215], v155 offset:5120
	ds_read_b128 v[216:219], v155 offset:6144
	ds_read_b128 v[220:223], v155 offset:7168
	global_load_lds_dwordx4 v[160:161], off
	v_lshl_add_u64 v[160:161], s[72:73], 0, v[140:141]
	s_add_i32 m0, s23, 0xe000
	s_nop 0
	global_load_lds_dwordx4 v[160:161], off
	s_waitcnt vmcnt(8)
	s_waitcnt lgkmcnt(0)
	s_barrier
	s_setprio 1
	s_waitcnt lgkmcnt(0)
	v_mfma_f32_16x16x32_bf16 v[126:129], v[146:149], v[192:195], v[126:129]
	v_mfma_f32_16x16x32_bf16 v[122:125], v[166:169], v[192:195], v[122:125]
	v_mfma_f32_16x16x32_bf16 v[118:121], v[146:149], v[200:203], v[118:121]
	v_mfma_f32_16x16x32_bf16 v[110:113], v[166:169], v[200:203], v[110:113]
	v_mfma_f32_16x16x32_bf16 v[102:105], v[146:149], v[208:211], v[102:105]
	v_mfma_f32_16x16x32_bf16 v[94:97], v[166:169], v[208:211], v[94:97]
	v_mfma_f32_16x16x32_bf16 v[86:89], v[146:149], v[216:219], v[86:89]
	v_mfma_f32_16x16x32_bf16 v[78:81], v[166:169], v[216:219], v[78:81]
	v_mfma_f32_16x16x32_bf16 v[126:129], v[156:159], v[196:199], v[126:129]
	v_mfma_f32_16x16x32_bf16 v[122:125], v[170:173], v[196:199], v[122:125]
	v_mfma_f32_16x16x32_bf16 v[118:121], v[156:159], v[204:207], v[118:121]
	v_mfma_f32_16x16x32_bf16 v[110:113], v[170:173], v[204:207], v[110:113]
	v_mfma_f32_16x16x32_bf16 v[102:105], v[156:159], v[212:215], v[102:105]
	v_mfma_f32_16x16x32_bf16 v[94:97], v[170:173], v[212:215], v[94:97]
	v_mfma_f32_16x16x32_bf16 v[86:89], v[156:159], v[220:223], v[86:89]
	v_mfma_f32_16x16x32_bf16 v[78:81], v[170:173], v[220:223], v[78:81]
	s_setprio 0
	s_setprio 1
	v_mfma_f32_16x16x32_bf16 v[114:117], v[174:177], v[192:195], v[114:117]
	v_mfma_f32_16x16x32_bf16 v[106:109], v[182:185], v[192:195], v[106:109]
	v_mfma_f32_16x16x32_bf16 v[98:101], v[174:177], v[200:203], v[98:101]
	v_mfma_f32_16x16x32_bf16 v[90:93], v[182:185], v[200:203], v[90:93]
	v_mfma_f32_16x16x32_bf16 v[82:85], v[174:177], v[208:211], v[82:85]
	v_mfma_f32_16x16x32_bf16 v[74:77], v[182:185], v[208:211], v[74:77]
	v_mfma_f32_16x16x32_bf16 v[70:73], v[174:177], v[216:219], v[70:73]
	v_mfma_f32_16x16x32_bf16 v[66:69], v[182:185], v[216:219], v[66:69]
	v_mfma_f32_16x16x32_bf16 v[114:117], v[178:181], v[196:199], v[114:117]
	v_mfma_f32_16x16x32_bf16 v[106:109], v[186:189], v[196:199], v[106:109]
	v_mfma_f32_16x16x32_bf16 v[98:101], v[178:181], v[204:207], v[98:101]
	v_mfma_f32_16x16x32_bf16 v[90:93], v[186:189], v[204:207], v[90:93]
	v_mfma_f32_16x16x32_bf16 v[82:85], v[178:181], v[212:215], v[82:85]
	v_mfma_f32_16x16x32_bf16 v[74:77], v[186:189], v[212:215], v[74:77]
	v_mfma_f32_16x16x32_bf16 v[70:73], v[178:181], v[220:223], v[70:73]
	v_mfma_f32_16x16x32_bf16 v[66:69], v[186:189], v[220:223], v[66:69]
	s_setprio 2
	s_barrier
	s_add_i32 s92, s88, s27
	v_lshl_add_u64 v[160:161], s[74:75], 0, v[132:133]
	s_mov_b32 m0, s92
	ds_read_b128 v[192:195], v155 offset:16384
	ds_read_b128 v[196:199], v155 offset:17408
	ds_read_b128 v[200:203], v155 offset:18432
	ds_read_b128 v[204:207], v155 offset:19456
	ds_read_b128 v[208:211], v155 offset:20480
	ds_read_b128 v[212:215], v155 offset:21504
	ds_read_b128 v[216:219], v155 offset:22528
	ds_read_b128 v[220:223], v155 offset:23552
	global_load_lds_dwordx4 v[160:161], off
	s_add_i32 m0, s92, 0x2000
	s_add_u32 s92, s74, 0x100000
	v_lshl_add_u64 v[224:225], s[74:75], 0, v[136:137]
	s_addc_u32 s93, s75, 0
	s_add_i32 s94, s89, s27
	global_load_lds_dwordx4 v[224:225], off
	v_lshl_add_u64 v[226:227], s[92:93], 0, v[132:133]
	s_mov_b32 m0, s94
	v_lshl_add_u64 v[228:229], s[76:77], 0, v[134:135]
	global_load_lds_dwordx4 v[226:227], off
	v_lshl_add_u64 v[226:227], s[92:93], 0, v[136:137]
	s_add_i32 m0, s94, 0x2000
	s_nop 0
	global_load_lds_dwordx4 v[226:227], off
	v_lshl_add_u64 v[226:227], s[76:77], 0, v[130:131]
	s_mov_b32 m0, s23
	s_nop 0
	global_load_lds_dwordx4 v[226:227], off
	s_mov_b32 m0, s26
	s_nop 0
	global_load_lds_dwordx4 v[228:229], off
	s_waitcnt vmcnt(8)
	s_waitcnt lgkmcnt(0)
	s_barrier
; #define PG8_STAGE(bufoff, gbase, voff) do { if constexpr (DIAG >= 1) break; _Pragma("unroll") for (int _i = 0; _i < 2; ++_i) \
;         __builtin_amdgcn_global_load_lds((const unsigned*)((const char*)(gbase) + (voff)[_i]), (PG8_LAS unsigned*)(lds + (bufoff) + ldsw + _i * 8192), 16, 0, 0); } while (0)
; #define PG8_LDA(dst, b, h) do { if constexpr (DIAG == 2 || DIAG == 3) break; _Pragma("unroll") for (int m = 0; m < 4; ++m) _Pragma("unroll") for (int k = 0; k < 2; ++k) dst[m][k] = *(const PG8_LAS bf16x8*)(lds + PG8_SA(b, h) + aoff + m * 2048 + k * 1024); } while (0)
; #define PG8_LDB(dst, b, h) do { if constexpr (DIAG == 2 || DIAG == 3) break; _Pragma("unroll") for (int n = 0; n < 2; ++n) _Pragma("unroll") for (int k = 0; k < 2; ++k) dst[n][k] = *(const PG8_LAS bf16x8*)(lds + PG8_SB(b, h) + boff + n * 2048 + k * 1024); } while (0)
; #define PG8_WAIT_V(n) asm volatile("s_waitcnt vmcnt(" #n ")" ::: "memory")
; #define PG8_WAIT_L(n) asm volatile("s_waitcnt lgkmcnt(" #n ")" ::: "memory")
; #define PG8_BAR __builtin_amdgcn_s_barrier()
; #define PG8_LP_ON __builtin_amdgcn_s_setprio(PG8_LOADPRIO)
; #define PG8_LP_OFF __builtin_amdgcn_s_setprio(0)
; #define PG8_LP_ON do {} while (0)
; #define PG8_LP_OFF do {} while (0)
;     ...
;             if constexpr (SP2) {
;             PG8_LP_ON; PG8_LDB(B0, 0, 0); PG8_LDB(B1, 0, 1); PG8_SCHED; PG8_LDA(At, 0, 0); PG8_STAGE(PG8_SA(1, 1), a1 + hstep, voffA);
;             PG8_LP_OFF; PG8_WAIT_V(8); PG8_WAIT_L(0); PG8_BAR; PG8_MMA(0, 0, At, B0); PG8_MMA(0, 1, At, B1); PG8_BAR; PG8_SCHED;
;             PG8_LP_ON; PG8_LDA(At, 0, 1); PG8_STAGE(PG8_SB(0, 0), b2, voffB); PG8_STAGE(PG8_SB(0, 1), b2 + hstep, voffB); PG8_STAGE(PG8_SA(0, 0), a2, voffA);
;             PG8_LP_OFF; PG8_WAIT_V(8); PG8_WAIT_L(0); PG8_BAR; PG8_MMA(1, 0, At, B0); PG8_MMA(1, 1, At, B1); PG8_BAR; PG8_SCHED;
;             PG8_LP_ON; PG8_LDB(B0, 1, 0); PG8_LDB(B1, 1, 1); PG8_SCHED; PG8_LDA(At, 1, 0); PG8_STAGE(PG8_SA(0, 1), a2 + hstep, voffA);
;             PG8_LP_OFF; PG8_WAIT_V(8); PG8_WAIT_L(0); PG8_BAR; PG8_MMA(0, 0, At, B0); PG8_MMA(0, 1, At, B1); PG8_BAR; PG8_SCHED;
;             PG8_LP_ON; PG8_LDA(At, 1, 1); PG8_STAGE(PG8_SB(1, 0), b3, voffB); PG8_STAGE(PG8_SB(1, 1), b3 + hstep, voffB); PG8_STAGE(PG8_SA(1, 0), a3, voffA);
;             PG8_LP_OFF; PG8_WAIT_V(8); PG8_WAIT_L(0); PG8_BAR; PG8_MMA(1, 0, At, B0); PG8_MMA(1, 1, At, B1); PG8_BAR; PG8_SCHED;
	s_setprio 1
	s_waitcnt lgkmcnt(0)
	v_mfma_f32_16x16x32_bf16 v[62:65], v[146:149], v[192:195], v[62:65]
	v_mfma_f32_16x16x32_bf16 v[58:61], v[166:169], v[192:195], v[58:61]
	v_mfma_f32_16x16x32_bf16 v[54:57], v[146:149], v[200:203], v[54:57]
	v_mfma_f32_16x16x32_bf16 v[46:49], v[166:169], v[200:203], v[46:49]
	v_mfma_f32_16x16x32_bf16 v[38:41], v[146:149], v[208:211], v[38:41]
	v_mfma_f32_16x16x32_bf16 v[30:33], v[166:169], v[208:211], v[30:33]
	v_mfma_f32_16x16x32_bf16 v[22:25], v[146:149], v[216:219], v[22:25]
	v_mfma_f32_16x16x32_bf16 v[14:17], v[166:169], v[216:219], v[14:17]
	v_mfma_f32_16x16x32_bf16 v[62:65], v[156:159], v[196:199], v[62:65]
	v_mfma_f32_16x16x32_bf16 v[58:61], v[170:173], v[196:199], v[58:61]
	v_mfma_f32_16x16x32_bf16 v[54:57], v[156:159], v[204:207], v[54:57]
	v_mfma_f32_16x16x32_bf16 v[46:49], v[170:173], v[204:207], v[46:49]
	v_mfma_f32_16x16x32_bf16 v[38:41], v[156:159], v[212:215], v[38:41]
	v_mfma_f32_16x16x32_bf16 v[30:33], v[170:173], v[212:215], v[30:33]
	v_mfma_f32_16x16x32_bf16 v[22:25], v[156:159], v[220:223], v[22:25]
	v_mfma_f32_16x16x32_bf16 v[14:17], v[170:173], v[220:223], v[14:17]
	s_setprio 0
	s_setprio 1
	v_mfma_f32_16x16x32_bf16 v[50:53], v[174:177], v[192:195], v[50:53]
	v_mfma_f32_16x16x32_bf16 v[42:45], v[182:185], v[192:195], v[42:45]
	v_mfma_f32_16x16x32_bf16 v[34:37], v[174:177], v[200:203], v[34:37]
	v_mfma_f32_16x16x32_bf16 v[26:29], v[182:185], v[200:203], v[26:29]
	v_mfma_f32_16x16x32_bf16 v[18:21], v[174:177], v[208:211], v[18:21]
	v_mfma_f32_16x16x32_bf16 v[10:13], v[182:185], v[208:211], v[10:13]
	v_mfma_f32_16x16x32_bf16 v[6:9], v[174:177], v[216:219], v[6:9]
	v_mfma_f32_16x16x32_bf16 v[2:5], v[182:185], v[216:219], v[2:5]
	v_mfma_f32_16x16x32_bf16 v[50:53], v[178:181], v[196:199], v[50:53]
	v_mfma_f32_16x16x32_bf16 v[42:45], v[186:189], v[196:199], v[42:45]
	v_mfma_f32_16x16x32_bf16 v[34:37], v[178:181], v[204:207], v[34:37]
	v_mfma_f32_16x16x32_bf16 v[26:29], v[186:189], v[204:207], v[26:29]
	v_mfma_f32_16x16x32_bf16 v[18:21], v[178:181], v[212:215], v[18:21]
	v_mfma_f32_16x16x32_bf16 v[10:13], v[186:189], v[212:215], v[10:13]
	v_mfma_f32_16x16x32_bf16 v[6:9], v[178:181], v[220:223], v[6:9]
	v_mfma_f32_16x16x32_bf16 v[2:5], v[186:189], v[220:223], v[2:5]
	s_setprio 2
	s_barrier
	s_add_i32 s92, 0, 0x18000
	v_add_u32_e32 v165, s92, v151
	s_add_i32 s93, 0, 0x1c000
	ds_read_b128 v[146:149], v165
	ds_read_b128 v[156:159], v165 offset:1024
	ds_read_b128 v[166:169], v165 offset:2048
	ds_read_b128 v[170:173], v165 offset:3072
	v_add_u32_e32 v165, s93, v151
	ds_read_b128 v[174:177], v165
	ds_read_b128 v[178:181], v165 offset:1024
	ds_read_b128 v[182:185], v165 offset:2048
	ds_read_b128 v[186:189], v165 offset:3072
	s_add_u32 s76, s76, 0x100000
	s_addc_u32 s77, s77, 0
	s_mov_b32 m0, s55
	v_lshl_add_u64 v[230:231], s[76:77], 0, v[130:131]
	ds_read_b128 v[192:195], v155 offset:32768
	ds_read_b128 v[196:199], v155 offset:33792
	ds_read_b128 v[200:203], v155 offset:34816
	ds_read_b128 v[204:207], v155 offset:35840
	ds_read_b128 v[208:211], v155 offset:36864
	ds_read_b128 v[212:215], v155 offset:37888
	ds_read_b128 v[216:219], v155 offset:38912
	ds_read_b128 v[220:223], v155 offset:39936
	global_load_lds_dwordx4 v[230:231], off
	v_lshl_add_u64 v[230:231], s[76:77], 0, v[134:135]
	s_mov_b32 m0, s84
	s_nop 0
	global_load_lds_dwordx4 v[230:231], off
	s_waitcnt vmcnt(8)
	s_waitcnt lgkmcnt(0)
	s_barrier
	s_setprio 1
	s_waitcnt lgkmcnt(0)
	v_mfma_f32_16x16x32_bf16 v[126:129], v[146:149], v[192:195], v[126:129]
	v_mfma_f32_16x16x32_bf16 v[122:125], v[166:169], v[192:195], v[122:125]
	v_mfma_f32_16x16x32_bf16 v[118:121], v[146:149], v[200:203], v[118:121]
	v_mfma_f32_16x16x32_bf16 v[110:113], v[166:169], v[200:203], v[110:113]
	v_mfma_f32_16x16x32_bf16 v[102:105], v[146:149], v[208:211], v[102:105]
	v_mfma_f32_16x16x32_bf16 v[94:97], v[166:169], v[208:211], v[94:97]
	v_mfma_f32_16x16x32_bf16 v[86:89], v[146:149], v[216:219], v[86:89]
	v_mfma_f32_16x16x32_bf16 v[78:81], v[166:169], v[216:219], v[78:81]
	v_mfma_f32_16x16x32_bf16 v[126:129], v[156:159], v[196:199], v[126:129]
	v_mfma_f32_16x16x32_bf16 v[122:125], v[170:173], v[196:199], v[122:125]
	v_mfma_f32_16x16x32_bf16 v[118:121], v[156:159], v[204:207], v[118:121]
	v_mfma_f32_16x16x32_bf16 v[110:113], v[170:173], v[204:207], v[110:113]
	v_mfma_f32_16x16x32_bf16 v[102:105], v[156:159], v[212:215], v[102:105]
	v_mfma_f32_16x16x32_bf16 v[94:97], v[170:173], v[212:215], v[94:97]
	v_mfma_f32_16x16x32_bf16 v[86:89], v[156:159], v[220:223], v[86:89]
	v_mfma_f32_16x16x32_bf16 v[78:81], v[170:173], v[220:223], v[78:81]
	s_setprio 0
	s_setprio 1
	v_mfma_f32_16x16x32_bf16 v[114:117], v[174:177], v[192:195], v[114:117]
	v_mfma_f32_16x16x32_bf16 v[106:109], v[182:185], v[192:195], v[106:109]
	v_mfma_f32_16x16x32_bf16 v[98:101], v[174:177], v[200:203], v[98:101]
	v_mfma_f32_16x16x32_bf16 v[90:93], v[182:185], v[200:203], v[90:93]
	v_mfma_f32_16x16x32_bf16 v[82:85], v[174:177], v[208:211], v[82:85]
	v_mfma_f32_16x16x32_bf16 v[74:77], v[182:185], v[208:211], v[74:77]
	v_mfma_f32_16x16x32_bf16 v[70:73], v[174:177], v[216:219], v[70:73]
	v_mfma_f32_16x16x32_bf16 v[66:69], v[182:185], v[216:219], v[66:69]
	v_mfma_f32_16x16x32_bf16 v[114:117], v[178:181], v[196:199], v[114:117]
	v_mfma_f32_16x16x32_bf16 v[106:109], v[186:189], v[196:199], v[106:109]
	v_mfma_f32_16x16x32_bf16 v[98:101], v[178:181], v[204:207], v[98:101]
	v_mfma_f32_16x16x32_bf16 v[90:93], v[186:189], v[204:207], v[90:93]
	v_mfma_f32_16x16x32_bf16 v[82:85], v[178:181], v[212:215], v[82:85]
	v_mfma_f32_16x16x32_bf16 v[74:77], v[186:189], v[212:215], v[74:77]
	v_mfma_f32_16x16x32_bf16 v[70:73], v[178:181], v[220:223], v[70:73]
	v_mfma_f32_16x16x32_bf16 v[66:69], v[186:189], v[220:223], v[66:69]
	s_setprio 2
	s_barrier
; #define PG8_STAGE(bufoff, gbase, voff) do { if constexpr (DIAG >= 1) break; _Pragma("unroll") for (int _i = 0; _i < 2; ++_i) \
;         __builtin_amdgcn_global_load_lds((const unsigned*)((const char*)(gbase) + (voff)[_i]), (PG8_LAS unsigned*)(lds + (bufoff) + ldsw + _i * 8192), 16, 0, 0); } while (0)
; #define PG8_LDA(dst, b, h) do { if constexpr (DIAG == 2 || DIAG == 3) break; _Pragma("unroll") for (int m = 0; m < 4; ++m) _Pragma("unroll") for (int k = 0; k < 2; ++k) dst[m][k] = *(const PG8_LAS bf16x8*)(lds + PG8_SA(b, h) + aoff + m * 2048 + k * 1024); } while (0)
; #define PG8_WAIT_V(n) asm volatile("s_waitcnt vmcnt(" #n ")" ::: "memory")
; #define PG8_WAIT_L(n) asm volatile("s_waitcnt lgkmcnt(" #n ")" ::: "memory")
; #define PG8_BAR __builtin_amdgcn_s_barrier()
; #define PG8_LP_OFF __builtin_amdgcn_s_setprio(0)
;     ...
;         for (int t = kb; t < ke; t += 2) {
;             const bool last = (t == ke - 2);
;             const char* a1 = cA + (size_t)(t + 1) * kstep;
;             const char* a2 = last ? nA : cA + (size_t)(t + 2) * kstep; const char* b2 = last ? nB : cB + (size_t)(t + 2) * kstep;
;             const char* a3 = a2 + kstep; const char* b3 = b2 + kstep;
;             if (last && has_next) S.a_ready(nxt);
;             if constexpr (SP2) {
;             PG8_LP_ON; PG8_LDB(B0, 0, 0); PG8_LDB(B1, 0, 1); PG8_SCHED; PG8_LDA(At, 0, 0); PG8_STAGE(PG8_SA(1, 1), a1 + hstep, voffA);
;             PG8_LP_OFF; PG8_WAIT_V(8); PG8_WAIT_L(0); PG8_BAR; PG8_MMA(0, 0, At, B0); PG8_MMA(0, 1, At, B1); PG8_BAR; PG8_SCHED;
;             PG8_LP_ON; PG8_LDA(At, 0, 1); PG8_STAGE(PG8_SB(0, 0), b2, voffB); PG8_STAGE(PG8_SB(0, 1), b2 + hstep, voffB); PG8_STAGE(PG8_SA(0, 0), a2, voffA);
;             PG8_LP_OFF; PG8_WAIT_V(8); PG8_WAIT_L(0); PG8_BAR; PG8_MMA(1, 0, At, B0); PG8_MMA(1, 1, At, B1); PG8_BAR; PG8_SCHED;
;             PG8_LP_ON; PG8_LDB(B0, 1, 0); PG8_LDB(B1, 1, 1); PG8_SCHED; PG8_LDA(At, 1, 0); PG8_STAGE(PG8_SA(0, 1), a2 + hstep, voffA);
;             PG8_LP_OFF; PG8_WAIT_V(8); PG8_WAIT_L(0); PG8_BAR; PG8_MMA(0, 0, At, B0); PG8_MMA(0, 1, At, B1); PG8_BAR; PG8_SCHED;
;             PG8_LP_ON; PG8_LDA(At, 1, 1); PG8_STAGE(PG8_SB(1, 0), b3, voffB); PG8_STAGE(PG8_SB(1, 1), b3 + hstep, voffB); PG8_STAGE(PG8_SA(1, 0), a3, voffA);
;             PG8_LP_OFF; PG8_WAIT_V(8); PG8_WAIT_L(0); PG8_BAR; PG8_MMA(1, 0, At, B0); PG8_MMA(1, 1, At, B1); PG8_BAR; PG8_SCHED;
	s_add_i32 s76, s92, s27
	v_lshl_add_u64 v[160:161], v[160:161], 0, s[10:11]
	s_mov_b32 m0, s76
	ds_read_b128 v[192:195], v155 offset:49152
	ds_read_b128 v[196:199], v155 offset:50176
	ds_read_b128 v[200:203], v155 offset:51200
	ds_read_b128 v[204:207], v155 offset:52224
	ds_read_b128 v[208:211], v155 offset:53248
	ds_read_b128 v[212:215], v155 offset:54272
	ds_read_b128 v[216:219], v155 offset:55296
	ds_read_b128 v[220:223], v155 offset:56320
	global_load_lds_dwordx4 v[160:161], off
	s_add_i32 m0, s76, 0x2000
	s_add_u32 s74, s74, 0x100080
	v_lshl_add_u64 v[160:161], v[224:225], 0, s[10:11]
	s_addc_u32 s75, s75, 0
	s_add_i32 s76, s93, s27
	global_load_lds_dwordx4 v[160:161], off
	v_lshl_add_u64 v[160:161], s[74:75], 0, v[132:133]
	s_mov_b32 m0, s76
	s_nop 0
	global_load_lds_dwordx4 v[160:161], off
	v_lshl_add_u64 v[160:161], s[74:75], 0, v[136:137]
	s_add_i32 m0, s76, 0x2000
	s_nop 0
	global_load_lds_dwordx4 v[160:161], off
	v_lshl_add_u64 v[160:161], v[226:227], 0, s[10:11]
	s_mov_b32 m0, s86
	s_nop 0
	global_load_lds_dwordx4 v[160:161], off
	v_lshl_add_u64 v[160:161], v[228:229], 0, s[10:11]
	s_mov_b32 m0, s87
	s_nop 0
	global_load_lds_dwordx4 v[160:161], off
	s_waitcnt vmcnt(8)
	s_waitcnt lgkmcnt(0)
	s_barrier
	s_setprio 1
	s_waitcnt lgkmcnt(0)
	v_mfma_f32_16x16x32_bf16 v[62:65], v[146:149], v[192:195], v[62:65]
	v_mfma_f32_16x16x32_bf16 v[58:61], v[166:169], v[192:195], v[58:61]
	v_mfma_f32_16x16x32_bf16 v[54:57], v[146:149], v[200:203], v[54:57]
	v_mfma_f32_16x16x32_bf16 v[46:49], v[166:169], v[200:203], v[46:49]
	v_mfma_f32_16x16x32_bf16 v[38:41], v[146:149], v[208:211], v[38:41]
	v_mfma_f32_16x16x32_bf16 v[30:33], v[166:169], v[208:211], v[30:33]
	v_mfma_f32_16x16x32_bf16 v[22:25], v[146:149], v[216:219], v[22:25]
	v_mfma_f32_16x16x32_bf16 v[14:17], v[166:169], v[216:219], v[14:17]
	v_mfma_f32_16x16x32_bf16 v[62:65], v[156:159], v[196:199], v[62:65]
	v_mfma_f32_16x16x32_bf16 v[58:61], v[170:173], v[196:199], v[58:61]
	v_mfma_f32_16x16x32_bf16 v[54:57], v[156:159], v[204:207], v[54:57]
	v_mfma_f32_16x16x32_bf16 v[46:49], v[170:173], v[204:207], v[46:49]
	v_mfma_f32_16x16x32_bf16 v[38:41], v[156:159], v[212:215], v[38:41]
	v_mfma_f32_16x16x32_bf16 v[30:33], v[170:173], v[212:215], v[30:33]
	v_mfma_f32_16x16x32_bf16 v[22:25], v[156:159], v[220:223], v[22:25]
	v_mfma_f32_16x16x32_bf16 v[14:17], v[170:173], v[220:223], v[14:17]
	s_setprio 0
	s_setprio 1
	v_mfma_f32_16x16x32_bf16 v[50:53], v[174:177], v[192:195], v[50:53]
	v_mfma_f32_16x16x32_bf16 v[42:45], v[182:185], v[192:195], v[42:45]
	v_mfma_f32_16x16x32_bf16 v[34:37], v[174:177], v[200:203], v[34:37]
	v_mfma_f32_16x16x32_bf16 v[26:29], v[182:185], v[200:203], v[26:29]
	v_mfma_f32_16x16x32_bf16 v[18:21], v[174:177], v[208:211], v[18:21]
	v_mfma_f32_16x16x32_bf16 v[10:13], v[182:185], v[208:211], v[10:13]
	v_mfma_f32_16x16x32_bf16 v[6:9], v[174:177], v[216:219], v[6:9]
	v_mfma_f32_16x16x32_bf16 v[2:5], v[182:185], v[216:219], v[2:5]
	v_mfma_f32_16x16x32_bf16 v[50:53], v[178:181], v[196:199], v[50:53]
	v_mfma_f32_16x16x32_bf16 v[42:45], v[186:189], v[196:199], v[42:45]
	v_mfma_f32_16x16x32_bf16 v[34:37], v[178:181], v[204:207], v[34:37]
	v_mfma_f32_16x16x32_bf16 v[26:29], v[186:189], v[204:207], v[26:29]
	v_mfma_f32_16x16x32_bf16 v[18:21], v[178:181], v[212:215], v[18:21]
	v_mfma_f32_16x16x32_bf16 v[10:13], v[186:189], v[212:215], v[10:13]
	v_mfma_f32_16x16x32_bf16 v[6:9], v[178:181], v[220:223], v[6:9]
	v_mfma_f32_16x16x32_bf16 v[2:5], v[186:189], v[220:223], v[2:5]
	s_setprio 2
	s_barrier
	s_add_i32 s91, s91, 2
	s_add_u32 s72, s72, 0x100
	s_addc_u32 s73, s73, 0
	s_add_u32 s82, s82, 0x100
	s_addc_u32 s83, s83, 0
	s_cmp_gt_u32 s91, 61
	s_cbranch_scc0 .LBB0_521
	s_and_b64 vcc, exec, s[12:13]
	s_cbranch_vccz .LBB0_524
	s_barrier

; #define PG8_STAGE(bufoff, gbase, voff) do { if constexpr (DIAG >= 1) break; _Pragma("unroll") for (int _i = 0; _i < 2; ++_i) \
;         __builtin_amdgcn_global_load_lds((const unsigned*)((const char*)(gbase) + (voff)[_i]), (PG8_LAS unsigned*)(lds + (bufoff) + ldsw + _i * 8192), 16, 0, 0); } while (0)
; #define PG8_LDA(dst, b, h) do { if constexpr (DIAG == 2 || DIAG == 3) break; _Pragma("unroll") for (int m = 0; m < 4; ++m) _Pragma("unroll") for (int k = 0; k < 2; ++k) dst[m][k] = *(const PG8_LAS bf16x8*)(lds + PG8_SA(b, h) + aoff + m * 2048 + k * 1024); } while (0)
; #define PG8_WAIT_V(n) asm volatile("s_waitcnt vmcnt(" #n ")" ::: "memory")
; #define PG8_WAIT_L(n) asm volatile("s_waitcnt lgkmcnt(" #n ")" ::: "memory")
; #define PG8_BAR __builtin_amdgcn_s_barrier()
; #define PG8_LP_OFF __builtin_amdgcn_s_setprio(0)
;     ...
;         for (int t = kb; t < ke; t += 2) {
;             const bool last = (t == ke - 2);
;             const char* a1 = cA + (size_t)(t + 1) * kstep;
;             const char* a2 = last ? nA : cA + (size_t)(t + 2) * kstep; const char* b2 = last ? nB : cB + (size_t)(t + 2) * kstep;
;             const char* a3 = a2 + kstep; const char* b3 = b2 + kstep;
;             if (last && has_next) S.a_ready(nxt);
;             if constexpr (SP2) {
;             PG8_LP_ON; PG8_LDB(B0, 0, 0); PG8_LDB(B1, 0, 1); PG8_SCHED; PG8_LDA(At, 0, 0); PG8_STAGE(PG8_SA(1, 1), a1 + hstep, voffA);
;             PG8_LP_OFF; PG8_WAIT_V(8); PG8_WAIT_L(0); PG8_BAR; PG8_MMA(0, 0, At, B0); PG8_MMA(0, 1, At, B1); PG8_BAR; PG8_SCHED;
;             PG8_LP_ON; PG8_LDA(At, 0, 1); PG8_STAGE(PG8_SB(0, 0), b2, voffB); PG8_STAGE(PG8_SB(0, 1), b2 + hstep, voffB); PG8_STAGE(PG8_SA(0, 0), a2, voffA);
;             PG8_LP_OFF; PG8_WAIT_V(8); PG8_WAIT_L(0); PG8_BAR; PG8_MMA(1, 0, At, B0); PG8_MMA(1, 1, At, B1); PG8_BAR; PG8_SCHED;
;             PG8_LP_ON; PG8_LDB(B0, 1, 0); PG8_LDB(B1, 1, 1); PG8_SCHED; PG8_LDA(At, 1, 0); PG8_STAGE(PG8_SA(0, 1), a2 + hstep, voffA);
;             PG8_LP_OFF; PG8_WAIT_V(8); PG8_WAIT_L(0); PG8_BAR; PG8_MMA(0, 0, At, B0); PG8_MMA(0, 1, At, B1); PG8_BAR; PG8_SCHED;
;             PG8_LP_ON; PG8_LDA(At, 1, 1); PG8_STAGE(PG8_SB(1, 0), b3, voffB); PG8_STAGE(PG8_SB(1, 1), b3 + hstep, voffB); PG8_STAGE(PG8_SA(1, 0), a3, voffA);
;             PG8_LP_OFF; PG8_WAIT_V(8); PG8_WAIT_L(0); PG8_BAR; PG8_MMA(1, 0, At, B0); PG8_MMA(1, 1, At, B1); PG8_BAR; PG8_SCHED;
.LBB0_725:
	ds_read_b128 v[130:133], v177
	ds_read_b128 v[134:137], v177 offset:1024
	ds_read_b128 v[138:141], v177 offset:2048
	ds_read_b128 v[142:145], v177 offset:3072
	ds_read_b128 v[166:169], v178
	ds_read_b128 v[170:173], v178 offset:1024
	ds_read_b128 v[180:183], v178 offset:2048
	ds_read_b128 v[184:187], v178 offset:3072
	s_add_u32 s62, s60, 0xfff00080
	s_addc_u32 s63, s61, -1
	s_cmp_eq_u32 s83, 60
	s_cselect_b32 s65, s5, s63
	s_cselect_b32 s64, s26, s62
	s_cselect_b32 s63, s23, s82
	s_cselect_b32 s62, s27, s47
	v_lshl_add_u64 v[160:161], s[60:61], 0, v[152:153]
	s_add_i32 m0, s1, 0xc000
	ds_read_b128 v[188:191], v179
	ds_read_b128 v[192:195], v179 offset:1024
	ds_read_b128 v[196:199], v179 offset:2048
	ds_read_b128 v[200:203], v179 offset:3072
	ds_read_b128 v[204:207], v179 offset:4096
	ds_read_b128 v[208:211], v179 offset:5120
	ds_read_b128 v[212:215], v179 offset:6144
	ds_read_b128 v[216:219], v179 offset:7168
	global_load_lds_dwordx4 v[160:161], off
	v_lshl_add_u64 v[160:161], s[60:61], 0, v[154:155]
	s_add_i32 m0, s1, 0xe000
	s_nop 0
	global_load_lds_dwordx4 v[160:161], off
	s_waitcnt vmcnt(8)
	s_waitcnt lgkmcnt(0)
	s_barrier
	s_setprio 1
	s_waitcnt lgkmcnt(0)
	v_mfma_f32_16x16x32_bf16 v[126:129], v[130:133], v[188:191], v[126:129]
	v_mfma_f32_16x16x32_bf16 v[122:125], v[138:141], v[188:191], v[122:125]
	v_mfma_f32_16x16x32_bf16 v[110:113], v[130:133], v[196:199], v[110:113]
	v_mfma_f32_16x16x32_bf16 v[106:109], v[138:141], v[196:199], v[106:109]
	v_mfma_f32_16x16x32_bf16 v[94:97], v[130:133], v[204:207], v[94:97]
	v_mfma_f32_16x16x32_bf16 v[90:93], v[138:141], v[204:207], v[90:93]
	v_mfma_f32_16x16x32_bf16 v[78:81], v[130:133], v[212:215], v[78:81]
	v_mfma_f32_16x16x32_bf16 v[74:77], v[138:141], v[212:215], v[74:77]
	v_mfma_f32_16x16x32_bf16 v[126:129], v[134:137], v[192:195], v[126:129]
	v_mfma_f32_16x16x32_bf16 v[122:125], v[142:145], v[192:195], v[122:125]
	v_mfma_f32_16x16x32_bf16 v[110:113], v[134:137], v[200:203], v[110:113]
	v_mfma_f32_16x16x32_bf16 v[106:109], v[142:145], v[200:203], v[106:109]
	v_mfma_f32_16x16x32_bf16 v[94:97], v[134:137], v[208:211], v[94:97]
	v_mfma_f32_16x16x32_bf16 v[90:93], v[142:145], v[208:211], v[90:93]
	v_mfma_f32_16x16x32_bf16 v[78:81], v[134:137], v[216:219], v[78:81]
	v_mfma_f32_16x16x32_bf16 v[74:77], v[142:145], v[216:219], v[74:77]
	s_setprio 0
	s_setprio 1
	v_mfma_f32_16x16x32_bf16 v[118:121], v[166:169], v[188:191], v[118:121]
	v_mfma_f32_16x16x32_bf16 v[114:117], v[180:183], v[188:191], v[114:117]
	v_mfma_f32_16x16x32_bf16 v[102:105], v[166:169], v[196:199], v[102:105]
	v_mfma_f32_16x16x32_bf16 v[98:101], v[180:183], v[196:199], v[98:101]
	v_mfma_f32_16x16x32_bf16 v[86:89], v[166:169], v[204:207], v[86:89]
	v_mfma_f32_16x16x32_bf16 v[82:85], v[180:183], v[204:207], v[82:85]
	v_mfma_f32_16x16x32_bf16 v[70:73], v[166:169], v[212:215], v[70:73]
	v_mfma_f32_16x16x32_bf16 v[66:69], v[180:183], v[212:215], v[66:69]
	v_mfma_f32_16x16x32_bf16 v[118:121], v[170:173], v[192:195], v[118:121]
	v_mfma_f32_16x16x32_bf16 v[114:117], v[184:187], v[192:195], v[114:117]
	v_mfma_f32_16x16x32_bf16 v[102:105], v[170:173], v[200:203], v[102:105]
	v_mfma_f32_16x16x32_bf16 v[98:101], v[184:187], v[200:203], v[98:101]
	v_mfma_f32_16x16x32_bf16 v[86:89], v[170:173], v[208:211], v[86:89]
	v_mfma_f32_16x16x32_bf16 v[82:85], v[184:187], v[208:211], v[82:85]
	v_mfma_f32_16x16x32_bf16 v[70:73], v[170:173], v[216:219], v[70:73]
	v_mfma_f32_16x16x32_bf16 v[66:69], v[184:187], v[216:219], v[66:69]
	s_setprio 2
	s_barrier
	s_add_i32 s84, s78, s0
	v_lshl_add_u64 v[160:161], s[62:63], 0, v[146:147]
	s_mov_b32 m0, s84
	ds_read_b128 v[188:191], v179 offset:16384
	ds_read_b128 v[192:195], v179 offset:17408
	ds_read_b128 v[196:199], v179 offset:18432
	ds_read_b128 v[200:203], v179 offset:19456
	ds_read_b128 v[204:207], v179 offset:20480
	ds_read_b128 v[208:211], v179 offset:21504
	ds_read_b128 v[212:215], v179 offset:22528
	ds_read_b128 v[216:219], v179 offset:23552
	global_load_lds_dwordx4 v[160:161], off
	s_add_i32 m0, s84, 0x2000
	s_add_u32 s84, s62, 0x100000
	v_lshl_add_u64 v[174:175], s[62:63], 0, v[148:149]
	s_addc_u32 s85, s63, 0
	s_add_i32 s86, s79, s0
	global_load_lds_dwordx4 v[174:175], off
	v_lshl_add_u64 v[220:221], s[84:85], 0, v[146:147]
	s_mov_b32 m0, s86
	v_lshl_add_u64 v[222:223], s[64:65], 0, v[148:149]
	global_load_lds_dwordx4 v[220:221], off
	v_lshl_add_u64 v[220:221], s[84:85], 0, v[148:149]
	s_add_i32 m0, s86, 0x2000
	s_nop 0
	global_load_lds_dwordx4 v[220:221], off
	v_lshl_add_u64 v[220:221], s[64:65], 0, v[146:147]
	s_mov_b32 m0, s1
	s_nop 0
	global_load_lds_dwordx4 v[220:221], off
	s_mov_b32 m0, s34
	s_nop 0
	global_load_lds_dwordx4 v[222:223], off
	s_waitcnt vmcnt(8)
	s_waitcnt lgkmcnt(0)
	s_barrier
; #define PG8_STAGE(bufoff, gbase, voff) do { if constexpr (DIAG >= 1) break; _Pragma("unroll") for (int _i = 0; _i < 2; ++_i) \
;         __builtin_amdgcn_global_load_lds((const unsigned*)((const char*)(gbase) + (voff)[_i]), (PG8_LAS unsigned*)(lds + (bufoff) + ldsw + _i * 8192), 16, 0, 0); } while (0)
; #define PG8_LDA(dst, b, h) do { if constexpr (DIAG == 2 || DIAG == 3) break; _Pragma("unroll") for (int m = 0; m < 4; ++m) _Pragma("unroll") for (int k = 0; k < 2; ++k) dst[m][k] = *(const PG8_LAS bf16x8*)(lds + PG8_SA(b, h) + aoff + m * 2048 + k * 1024); } while (0)
; #define PG8_LDB(dst, b, h) do { if constexpr (DIAG == 2 || DIAG == 3) break; _Pragma("unroll") for (int n = 0; n < 2; ++n) _Pragma("unroll") for (int k = 0; k < 2; ++k) dst[n][k] = *(const PG8_LAS bf16x8*)(lds + PG8_SB(b, h) + boff + n * 2048 + k * 1024); } while (0)
; #define PG8_WAIT_V(n) asm volatile("s_waitcnt vmcnt(" #n ")" ::: "memory")
; #define PG8_WAIT_L(n) asm volatile("s_waitcnt lgkmcnt(" #n ")" ::: "memory")
; #define PG8_BAR __builtin_amdgcn_s_barrier()
; #define PG8_LP_ON __builtin_amdgcn_s_setprio(PG8_LOADPRIO)
; #define PG8_LP_OFF __builtin_amdgcn_s_setprio(0)
; #define PG8_LP_ON do {} while (0)
; #define PG8_LP_OFF do {} while (0)
;     ...
;             if constexpr (SP2) {
;             PG8_LP_ON; PG8_LDB(B0, 0, 0); PG8_LDB(B1, 0, 1); PG8_SCHED; PG8_LDA(At, 0, 0); PG8_STAGE(PG8_SA(1, 1), a1 + hstep, voffA);
;             PG8_LP_OFF; PG8_WAIT_V(8); PG8_WAIT_L(0); PG8_BAR; PG8_MMA(0, 0, At, B0); PG8_MMA(0, 1, At, B1); PG8_BAR; PG8_SCHED;
;             PG8_LP_ON; PG8_LDA(At, 0, 1); PG8_STAGE(PG8_SB(0, 0), b2, voffB); PG8_STAGE(PG8_SB(0, 1), b2 + hstep, voffB); PG8_STAGE(PG8_SA(0, 0), a2, voffA);
;             PG8_LP_OFF; PG8_WAIT_V(8); PG8_WAIT_L(0); PG8_BAR; PG8_MMA(1, 0, At, B0); PG8_MMA(1, 1, At, B1); PG8_BAR; PG8_SCHED;
;             PG8_LP_ON; PG8_LDB(B0, 1, 0); PG8_LDB(B1, 1, 1); PG8_SCHED; PG8_LDA(At, 1, 0); PG8_STAGE(PG8_SA(0, 1), a2 + hstep, voffA);
;             PG8_LP_OFF; PG8_WAIT_V(8); PG8_WAIT_L(0); PG8_BAR; PG8_MMA(0, 0, At, B0); PG8_MMA(0, 1, At, B1); PG8_BAR; PG8_SCHED;
;             PG8_LP_ON; PG8_LDA(At, 1, 1); PG8_STAGE(PG8_SB(1, 0), b3, voffB); PG8_STAGE(PG8_SB(1, 1), b3 + hstep, voffB); PG8_STAGE(PG8_SA(1, 0), a3, voffA);
;             PG8_LP_OFF; PG8_WAIT_V(8); PG8_WAIT_L(0); PG8_BAR; PG8_MMA(1, 0, At, B0); PG8_MMA(1, 1, At, B1); PG8_BAR; PG8_SCHED;
	s_setprio 1
	s_waitcnt lgkmcnt(0)
	v_mfma_f32_16x16x32_bf16 v[62:65], v[130:133], v[188:191], v[62:65]
	v_mfma_f32_16x16x32_bf16 v[58:61], v[138:141], v[188:191], v[58:61]
	v_mfma_f32_16x16x32_bf16 v[46:49], v[130:133], v[196:199], v[46:49]
	v_mfma_f32_16x16x32_bf16 v[42:45], v[138:141], v[196:199], v[42:45]
	v_mfma_f32_16x16x32_bf16 v[30:33], v[130:133], v[204:207], v[30:33]
	v_mfma_f32_16x16x32_bf16 v[26:29], v[138:141], v[204:207], v[26:29]
	v_mfma_f32_16x16x32_bf16 v[14:17], v[130:133], v[212:215], v[14:17]
	v_mfma_f32_16x16x32_bf16 v[10:13], v[138:141], v[212:215], v[10:13]
	v_mfma_f32_16x16x32_bf16 v[62:65], v[134:137], v[192:195], v[62:65]
	v_mfma_f32_16x16x32_bf16 v[58:61], v[142:145], v[192:195], v[58:61]
	v_mfma_f32_16x16x32_bf16 v[46:49], v[134:137], v[200:203], v[46:49]
	v_mfma_f32_16x16x32_bf16 v[42:45], v[142:145], v[200:203], v[42:45]
	v_mfma_f32_16x16x32_bf16 v[30:33], v[134:137], v[208:211], v[30:33]
	v_mfma_f32_16x16x32_bf16 v[26:29], v[142:145], v[208:211], v[26:29]
	v_mfma_f32_16x16x32_bf16 v[14:17], v[134:137], v[216:219], v[14:17]
	v_mfma_f32_16x16x32_bf16 v[10:13], v[142:145], v[216:219], v[10:13]
	s_setprio 0
	s_setprio 1
	v_mfma_f32_16x16x32_bf16 v[54:57], v[166:169], v[188:191], v[54:57]
	v_mfma_f32_16x16x32_bf16 v[50:53], v[180:183], v[188:191], v[50:53]
	v_mfma_f32_16x16x32_bf16 v[38:41], v[166:169], v[196:199], v[38:41]
	v_mfma_f32_16x16x32_bf16 v[34:37], v[180:183], v[196:199], v[34:37]
	v_mfma_f32_16x16x32_bf16 v[22:25], v[166:169], v[204:207], v[22:25]
	v_mfma_f32_16x16x32_bf16 v[18:21], v[180:183], v[204:207], v[18:21]
	v_mfma_f32_16x16x32_bf16 v[6:9], v[166:169], v[212:215], v[6:9]
	v_mfma_f32_16x16x32_bf16 v[2:5], v[180:183], v[212:215], v[2:5]
	v_mfma_f32_16x16x32_bf16 v[54:57], v[170:173], v[192:195], v[54:57]
	v_mfma_f32_16x16x32_bf16 v[50:53], v[184:187], v[192:195], v[50:53]
	v_mfma_f32_16x16x32_bf16 v[38:41], v[170:173], v[200:203], v[38:41]
	v_mfma_f32_16x16x32_bf16 v[34:37], v[184:187], v[200:203], v[34:37]
	v_mfma_f32_16x16x32_bf16 v[22:25], v[170:173], v[208:211], v[22:25]
	v_mfma_f32_16x16x32_bf16 v[18:21], v[184:187], v[208:211], v[18:21]
	v_mfma_f32_16x16x32_bf16 v[6:9], v[170:173], v[216:219], v[6:9]
	v_mfma_f32_16x16x32_bf16 v[2:5], v[184:187], v[216:219], v[2:5]
	s_setprio 2
	s_barrier
	s_add_i32 s84, 0, 0x18000
	s_add_i32 s85, 0, 0x1c000
	v_add_u32_e32 v142, s84, v165
	v_add_u32_e32 v150, s85, v165
	ds_read_b128 v[130:133], v142
	ds_read_b128 v[134:137], v142 offset:1024
	ds_read_b128 v[138:141], v142 offset:2048
	ds_read_b128 v[142:145], v142 offset:3072
	ds_read_b128 v[166:169], v150
	ds_read_b128 v[170:173], v150 offset:1024
	ds_read_b128 v[180:183], v150 offset:2048
	ds_read_b128 v[184:187], v150 offset:3072
	s_add_u32 s64, s64, 0x100000
	s_addc_u32 s65, s65, 0
	s_mov_b32 m0, s55
	v_lshl_add_u64 v[224:225], s[64:65], 0, v[146:147]
	ds_read_b128 v[188:191], v179 offset:32768
	ds_read_b128 v[192:195], v179 offset:33792
	ds_read_b128 v[196:199], v179 offset:34816
	ds_read_b128 v[200:203], v179 offset:35840
	ds_read_b128 v[204:207], v179 offset:36864
	ds_read_b128 v[208:211], v179 offset:37888
	ds_read_b128 v[212:215], v179 offset:38912
	ds_read_b128 v[216:219], v179 offset:39936
	global_load_lds_dwordx4 v[224:225], off
	v_lshl_add_u64 v[224:225], s[64:65], 0, v[148:149]
	s_mov_b32 m0, s66
	s_nop 0
	global_load_lds_dwordx4 v[224:225], off
	s_waitcnt vmcnt(8)
	s_waitcnt lgkmcnt(0)
	s_barrier
	s_setprio 1
	s_waitcnt lgkmcnt(0)
	v_mfma_f32_16x16x32_bf16 v[126:129], v[130:133], v[188:191], v[126:129]
	v_mfma_f32_16x16x32_bf16 v[122:125], v[138:141], v[188:191], v[122:125]
	v_mfma_f32_16x16x32_bf16 v[110:113], v[130:133], v[196:199], v[110:113]
	v_mfma_f32_16x16x32_bf16 v[106:109], v[138:141], v[196:199], v[106:109]
	v_mfma_f32_16x16x32_bf16 v[94:97], v[130:133], v[204:207], v[94:97]
	v_mfma_f32_16x16x32_bf16 v[90:93], v[138:141], v[204:207], v[90:93]
	v_mfma_f32_16x16x32_bf16 v[78:81], v[130:133], v[212:215], v[78:81]
	v_mfma_f32_16x16x32_bf16 v[74:77], v[138:141], v[212:215], v[74:77]
	v_mfma_f32_16x16x32_bf16 v[126:129], v[134:137], v[192:195], v[126:129]
	v_mfma_f32_16x16x32_bf16 v[122:125], v[142:145], v[192:195], v[122:125]
	v_mfma_f32_16x16x32_bf16 v[110:113], v[134:137], v[200:203], v[110:113]
	v_mfma_f32_16x16x32_bf16 v[106:109], v[142:145], v[200:203], v[106:109]
	v_mfma_f32_16x16x32_bf16 v[94:97], v[134:137], v[208:211], v[94:97]
	v_mfma_f32_16x16x32_bf16 v[90:93], v[142:145], v[208:211], v[90:93]
	v_mfma_f32_16x16x32_bf16 v[78:81], v[134:137], v[216:219], v[78:81]
	v_mfma_f32_16x16x32_bf16 v[74:77], v[142:145], v[216:219], v[74:77]
	s_setprio 0
	s_setprio 1
	v_mfma_f32_16x16x32_bf16 v[118:121], v[166:169], v[188:191], v[118:121]
	v_mfma_f32_16x16x32_bf16 v[114:117], v[180:183], v[188:191], v[114:117]
	v_mfma_f32_16x16x32_bf16 v[102:105], v[166:169], v[196:199], v[102:105]
	v_mfma_f32_16x16x32_bf16 v[98:101], v[180:183], v[196:199], v[98:101]
	v_mfma_f32_16x16x32_bf16 v[86:89], v[166:169], v[204:207], v[86:89]
	v_mfma_f32_16x16x32_bf16 v[82:85], v[180:183], v[204:207], v[82:85]
	v_mfma_f32_16x16x32_bf16 v[70:73], v[166:169], v[212:215], v[70:73]
	v_mfma_f32_16x16x32_bf16 v[66:69], v[180:183], v[212:215], v[66:69]
	v_mfma_f32_16x16x32_bf16 v[118:121], v[170:173], v[192:195], v[118:121]
	v_mfma_f32_16x16x32_bf16 v[114:117], v[184:187], v[192:195], v[114:117]
	v_mfma_f32_16x16x32_bf16 v[102:105], v[170:173], v[200:203], v[102:105]
	v_mfma_f32_16x16x32_bf16 v[98:101], v[184:187], v[200:203], v[98:101]
	v_mfma_f32_16x16x32_bf16 v[86:89], v[170:173], v[208:211], v[86:89]
	v_mfma_f32_16x16x32_bf16 v[82:85], v[184:187], v[208:211], v[82:85]
	v_mfma_f32_16x16x32_bf16 v[70:73], v[170:173], v[216:219], v[70:73]
	v_mfma_f32_16x16x32_bf16 v[66:69], v[184:187], v[216:219], v[66:69]
	s_setprio 2
	s_barrier
; #define PG8_STAGE(bufoff, gbase, voff) do { if constexpr (DIAG >= 1) break; _Pragma("unroll") for (int _i = 0; _i < 2; ++_i) \
;         __builtin_amdgcn_global_load_lds((const unsigned*)((const char*)(gbase) + (voff)[_i]), (PG8_LAS unsigned*)(lds + (bufoff) + ldsw + _i * 8192), 16, 0, 0); } while (0)
; #define PG8_LDA(dst, b, h) do { if constexpr (DIAG == 2 || DIAG == 3) break; _Pragma("unroll") for (int m = 0; m < 4; ++m) _Pragma("unroll") for (int k = 0; k < 2; ++k) dst[m][k] = *(const PG8_LAS bf16x8*)(lds + PG8_SA(b, h) + aoff + m * 2048 + k * 1024); } while (0)
; #define PG8_WAIT_V(n) asm volatile("s_waitcnt vmcnt(" #n ")" ::: "memory")
; #define PG8_WAIT_L(n) asm volatile("s_waitcnt lgkmcnt(" #n ")" ::: "memory")
; #define PG8_BAR __builtin_amdgcn_s_barrier()
; #define PG8_LP_OFF __builtin_amdgcn_s_setprio(0)
;     ...
;         for (int t = kb; t < ke; t += 2) {
;             const bool last = (t == ke - 2);
;             const char* a1 = cA + (size_t)(t + 1) * kstep;
;             const char* a2 = last ? nA : cA + (size_t)(t + 2) * kstep; const char* b2 = last ? nB : cB + (size_t)(t + 2) * kstep;
;             const char* a3 = a2 + kstep; const char* b3 = b2 + kstep;
;             if (last && has_next) S.a_ready(nxt);
;             if constexpr (SP2) {
;             PG8_LP_ON; PG8_LDB(B0, 0, 0); PG8_LDB(B1, 0, 1); PG8_SCHED; PG8_LDA(At, 0, 0); PG8_STAGE(PG8_SA(1, 1), a1 + hstep, voffA);
;             PG8_LP_OFF; PG8_WAIT_V(8); PG8_WAIT_L(0); PG8_BAR; PG8_MMA(0, 0, At, B0); PG8_MMA(0, 1, At, B1); PG8_BAR; PG8_SCHED;
;             PG8_LP_ON; PG8_LDA(At, 0, 1); PG8_STAGE(PG8_SB(0, 0), b2, voffB); PG8_STAGE(PG8_SB(0, 1), b2 + hstep, voffB); PG8_STAGE(PG8_SA(0, 0), a2, voffA);
;             PG8_LP_OFF; PG8_WAIT_V(8); PG8_WAIT_L(0); PG8_BAR; PG8_MMA(1, 0, At, B0); PG8_MMA(1, 1, At, B1); PG8_BAR; PG8_SCHED;
;             PG8_LP_ON; PG8_LDB(B0, 1, 0); PG8_LDB(B1, 1, 1); PG8_SCHED; PG8_LDA(At, 1, 0); PG8_STAGE(PG8_SA(0, 1), a2 + hstep, voffA);
;             PG8_LP_OFF; PG8_WAIT_V(8); PG8_WAIT_L(0); PG8_BAR; PG8_MMA(0, 0, At, B0); PG8_MMA(0, 1, At, B1); PG8_BAR; PG8_SCHED;
;             PG8_LP_ON; PG8_LDA(At, 1, 1); PG8_STAGE(PG8_SB(1, 0), b3, voffB); PG8_STAGE(PG8_SB(1, 1), b3 + hstep, voffB); PG8_STAGE(PG8_SA(1, 0), a3, voffA);
;             PG8_LP_OFF; PG8_WAIT_V(8); PG8_WAIT_L(0); PG8_BAR; PG8_MMA(1, 0, At, B0); PG8_MMA(1, 1, At, B1); PG8_BAR; PG8_SCHED;
	s_add_i32 s64, s84, s0
	v_lshl_add_u64 v[160:161], v[160:161], 0, s[14:15]
	s_mov_b32 m0, s64
	ds_read_b128 v[188:191], v179 offset:49152
	ds_read_b128 v[192:195], v179 offset:50176
	ds_read_b128 v[196:199], v179 offset:51200
	ds_read_b128 v[200:203], v179 offset:52224
	ds_read_b128 v[204:207], v179 offset:53248
	ds_read_b128 v[208:211], v179 offset:54272
	ds_read_b128 v[212:215], v179 offset:55296
	ds_read_b128 v[216:219], v179 offset:56320
	global_load_lds_dwordx4 v[160:161], off
	s_add_i32 m0, s64, 0x2000
	s_add_u32 s62, s62, 0x100080
	v_lshl_add_u64 v[160:161], v[174:175], 0, s[14:15]
	s_addc_u32 s63, s63, 0
	s_add_i32 s64, s85, s0
	global_load_lds_dwordx4 v[160:161], off
	v_lshl_add_u64 v[160:161], s[62:63], 0, v[146:147]
	s_mov_b32 m0, s64
	s_nop 0
	global_load_lds_dwordx4 v[160:161], off
	v_lshl_add_u64 v[160:161], s[62:63], 0, v[148:149]
	s_add_i32 m0, s64, 0x2000
	s_nop 0
	global_load_lds_dwordx4 v[160:161], off
	v_lshl_add_u64 v[160:161], v[220:221], 0, s[14:15]
	s_mov_b32 m0, s74
	s_nop 0
	global_load_lds_dwordx4 v[160:161], off
	v_lshl_add_u64 v[160:161], v[222:223], 0, s[14:15]
	s_mov_b32 m0, s75
	s_nop 0
	global_load_lds_dwordx4 v[160:161], off
	s_waitcnt vmcnt(8)
	s_waitcnt lgkmcnt(0)
	s_barrier
	s_setprio 1
	s_waitcnt lgkmcnt(0)
	v_mfma_f32_16x16x32_bf16 v[62:65], v[130:133], v[188:191], v[62:65]
	v_mfma_f32_16x16x32_bf16 v[58:61], v[138:141], v[188:191], v[58:61]
	v_mfma_f32_16x16x32_bf16 v[46:49], v[130:133], v[196:199], v[46:49]
	v_mfma_f32_16x16x32_bf16 v[42:45], v[138:141], v[196:199], v[42:45]
	v_mfma_f32_16x16x32_bf16 v[30:33], v[130:133], v[204:207], v[30:33]
	v_mfma_f32_16x16x32_bf16 v[26:29], v[138:141], v[204:207], v[26:29]
	v_mfma_f32_16x16x32_bf16 v[14:17], v[130:133], v[212:215], v[14:17]
	v_mfma_f32_16x16x32_bf16 v[10:13], v[138:141], v[212:215], v[10:13]
	v_mfma_f32_16x16x32_bf16 v[62:65], v[134:137], v[192:195], v[62:65]
	v_mfma_f32_16x16x32_bf16 v[58:61], v[142:145], v[192:195], v[58:61]
	v_mfma_f32_16x16x32_bf16 v[46:49], v[134:137], v[200:203], v[46:49]
	v_mfma_f32_16x16x32_bf16 v[42:45], v[142:145], v[200:203], v[42:45]
	v_mfma_f32_16x16x32_bf16 v[30:33], v[134:137], v[208:211], v[30:33]
	v_mfma_f32_16x16x32_bf16 v[26:29], v[142:145], v[208:211], v[26:29]
	v_mfma_f32_16x16x32_bf16 v[14:17], v[134:137], v[216:219], v[14:17]
	v_mfma_f32_16x16x32_bf16 v[10:13], v[142:145], v[216:219], v[10:13]
	s_setprio 0
	s_setprio 1
	v_mfma_f32_16x16x32_bf16 v[54:57], v[166:169], v[188:191], v[54:57]
	v_mfma_f32_16x16x32_bf16 v[50:53], v[180:183], v[188:191], v[50:53]
	v_mfma_f32_16x16x32_bf16 v[38:41], v[166:169], v[196:199], v[38:41]
	v_mfma_f32_16x16x32_bf16 v[34:37], v[180:183], v[196:199], v[34:37]
	v_mfma_f32_16x16x32_bf16 v[22:25], v[166:169], v[204:207], v[22:25]
	v_mfma_f32_16x16x32_bf16 v[18:21], v[180:183], v[204:207], v[18:21]
	v_mfma_f32_16x16x32_bf16 v[6:9], v[166:169], v[212:215], v[6:9]
	v_mfma_f32_16x16x32_bf16 v[2:5], v[180:183], v[212:215], v[2:5]
	v_mfma_f32_16x16x32_bf16 v[54:57], v[170:173], v[192:195], v[54:57]
	v_mfma_f32_16x16x32_bf16 v[50:53], v[184:187], v[192:195], v[50:53]
	v_mfma_f32_16x16x32_bf16 v[38:41], v[170:173], v[200:203], v[38:41]
	v_mfma_f32_16x16x32_bf16 v[34:37], v[184:187], v[200:203], v[34:37]
	v_mfma_f32_16x16x32_bf16 v[22:25], v[170:173], v[208:211], v[22:25]
	v_mfma_f32_16x16x32_bf16 v[18:21], v[184:187], v[208:211], v[18:21]
	v_mfma_f32_16x16x32_bf16 v[6:9], v[170:173], v[216:219], v[6:9]
	v_mfma_f32_16x16x32_bf16 v[2:5], v[184:187], v[216:219], v[2:5]
	s_setprio 2
	s_barrier
	s_add_i32 s83, s83, 2
	s_add_u32 s60, s60, 0x100
	s_addc_u32 s61, s61, 0
	s_add_u32 s47, s47, 0x100
	s_addc_u32 s82, s82, 0
	s_cmp_gt_u32 s83, 61
	s_cbranch_scc0 .LBB0_725
	s_and_b64 vcc, exec, s[16:17]
	s_cbranch_vccz .LBB0_728
	s_barrier

; #define PG8_STAGE(bufoff, gbase, voff) do { if constexpr (DIAG >= 1) break; _Pragma("unroll") for (int _i = 0; _i < 2; ++_i) \
;         __builtin_amdgcn_global_load_lds((const unsigned*)((const char*)(gbase) + (voff)[_i]), (PG8_LAS unsigned*)(lds + (bufoff) + ldsw + _i * 8192), 16, 0, 0); } while (0)
; #define PG8_LDA(dst, b, h) do { if constexpr (DIAG == 2 || DIAG == 3) break; _Pragma("unroll") for (int m = 0; m < 4; ++m) _Pragma("unroll") for (int k = 0; k < 2; ++k) dst[m][k] = *(const PG8_LAS bf16x8*)(lds + PG8_SA(b, h) + aoff + m * 2048 + k * 1024); } while (0)
; #define PG8_WAIT_V(n) asm volatile("s_waitcnt vmcnt(" #n ")" ::: "memory")
; #define PG8_WAIT_L(n) asm volatile("s_waitcnt lgkmcnt(" #n ")" ::: "memory")
; #define PG8_BAR __builtin_amdgcn_s_barrier()
; #define PG8_LP_OFF __builtin_amdgcn_s_setprio(0)
;     ...
;         for (int t = kb; t < ke; t += 2) {
;             const bool last = (t == ke - 2);
;             const char* a1 = cA + (size_t)(t + 1) * kstep;
;             const char* a2 = last ? nA : cA + (size_t)(t + 2) * kstep; const char* b2 = last ? nB : cB + (size_t)(t + 2) * kstep;
;             const char* a3 = a2 + kstep; const char* b3 = b2 + kstep;
;             if (last && has_next) S.a_ready(nxt);
;             if constexpr (SP2) {
;             PG8_LP_ON; PG8_LDB(B0, 0, 0); PG8_LDB(B1, 0, 1); PG8_SCHED; PG8_LDA(At, 0, 0); PG8_STAGE(PG8_SA(1, 1), a1 + hstep, voffA);
;             PG8_LP_OFF; PG8_WAIT_V(8); PG8_WAIT_L(0); PG8_BAR; PG8_MMA(0, 0, At, B0); PG8_MMA(0, 1, At, B1); PG8_BAR; PG8_SCHED;
;             PG8_LP_ON; PG8_LDA(At, 0, 1); PG8_STAGE(PG8_SB(0, 0), b2, voffB); PG8_STAGE(PG8_SB(0, 1), b2 + hstep, voffB); PG8_STAGE(PG8_SA(0, 0), a2, voffA);
;             PG8_LP_OFF; PG8_WAIT_V(8); PG8_WAIT_L(0); PG8_BAR; PG8_MMA(1, 0, At, B0); PG8_MMA(1, 1, At, B1); PG8_BAR; PG8_SCHED;
;             PG8_LP_ON; PG8_LDB(B0, 1, 0); PG8_LDB(B1, 1, 1); PG8_SCHED; PG8_LDA(At, 1, 0); PG8_STAGE(PG8_SA(0, 1), a2 + hstep, voffA);
;             PG8_LP_OFF; PG8_WAIT_V(8); PG8_WAIT_L(0); PG8_BAR; PG8_MMA(0, 0, At, B0); PG8_MMA(0, 1, At, B1); PG8_BAR; PG8_SCHED;
;             PG8_LP_ON; PG8_LDA(At, 1, 1); PG8_STAGE(PG8_SB(1, 0), b3, voffB); PG8_STAGE(PG8_SB(1, 1), b3 + hstep, voffB); PG8_STAGE(PG8_SA(1, 0), a3, voffA);
;             PG8_LP_OFF; PG8_WAIT_V(8); PG8_WAIT_L(0); PG8_BAR; PG8_MMA(1, 0, At, B0); PG8_MMA(1, 1, At, B1); PG8_BAR; PG8_SCHED;
.LBB0_918:
	s_add_i32 s4, s55, 1
	s_ashr_i32 s5, s4, 31
	s_lshl_b64 s[90:91], s[4:5], 7
	s_add_i32 s4, s55, 2
	s_ashr_i32 s5, s4, 31
	s_lshl_b64 s[70:71], s[4:5], 7
	s_add_u32 s5, s22, s70
	s_addc_u32 s72, s23, s71
	s_add_u32 s70, s20, s70
	s_addc_u32 s71, s21, s71
	s_add_i32 s92, 0, 0x10000
	s_cmp_eq_u32 s53, s55
	s_cselect_b32 s73, s26, s72
	s_cselect_b32 s72, s17, s5
	s_cselect_b32 s71, s49, s71
	s_cselect_b32 s70, s27, s70
	s_add_i32 s5, 0, 0x14000
	v_add_u32_e32 v14, s92, v184
	v_add_u32_e32 v30, s5, v184
	ds_read_b128 v[2:5], v14
	ds_read_b128 v[6:9], v14 offset:1024
	ds_read_b128 v[10:13], v14 offset:2048
	ds_read_b128 v[14:17], v14 offset:3072
	ds_read_b128 v[18:21], v30
	ds_read_b128 v[22:25], v30 offset:1024
	ds_read_b128 v[26:29], v30 offset:2048
	ds_read_b128 v[30:33], v30 offset:3072
	s_add_u32 s55, s22, s90
	s_addc_u32 s91, s23, s91
	s_add_u32 s90, s55, 0x80000
	s_addc_u32 s91, s91, 0
	v_lshl_add_u64 v[242:243], s[90:91], 0, v[172:173]
	s_add_i32 m0, s19, 0xc000
	ds_read_b128 v[174:177], v216
	ds_read_b128 v[178:181], v216 offset:1024
	ds_read_b128 v[218:221], v216 offset:2048
	ds_read_b128 v[222:225], v216 offset:3072
	ds_read_b128 v[226:229], v216 offset:4096
	ds_read_b128 v[230:233], v216 offset:5120
	ds_read_b128 v[234:237], v216 offset:6144
	ds_read_b128 v[238:241], v216 offset:7168
	global_load_lds_dwordx4 v[242:243], off
	v_lshl_add_u64 v[242:243], s[90:91], 0, v[168:169]
	s_add_i32 m0, s19, 0xe000
	s_nop 0
	global_load_lds_dwordx4 v[242:243], off
	s_waitcnt vmcnt(8)
	s_waitcnt lgkmcnt(0)
	s_barrier
	s_setprio 1
	s_waitcnt lgkmcnt(0)
	v_mfma_f32_16x16x128_f8f6f4 v[158:161], v[2:9], v[174:181], v[158:161]
	v_mfma_f32_16x16x128_f8f6f4 v[154:157], v[10:17], v[174:181], v[154:157]
	v_mfma_f32_16x16x128_f8f6f4 v[150:153], v[2:9], v[218:225], v[150:153]
	v_mfma_f32_16x16x128_f8f6f4 v[146:149], v[10:17], v[218:225], v[146:149]
	v_mfma_f32_16x16x128_f8f6f4 v[142:145], v[2:9], v[226:233], v[142:145]
	v_mfma_f32_16x16x128_f8f6f4 v[138:141], v[10:17], v[226:233], v[138:141]
	v_mfma_f32_16x16x128_f8f6f4 v[134:137], v[2:9], v[234:241], v[134:137]
	v_mfma_f32_16x16x128_f8f6f4 v[130:133], v[10:17], v[234:241], v[130:133]
	s_setprio 0
	s_setprio 1
	v_mfma_f32_16x16x128_f8f6f4 v[126:129], v[18:25], v[174:181], v[126:129]
	v_mfma_f32_16x16x128_f8f6f4 v[122:125], v[26:33], v[174:181], v[122:125]
	v_mfma_f32_16x16x128_f8f6f4 v[118:121], v[18:25], v[218:225], v[118:121]
	v_mfma_f32_16x16x128_f8f6f4 v[114:117], v[26:33], v[218:225], v[114:117]
	v_mfma_f32_16x16x128_f8f6f4 v[110:113], v[18:25], v[226:233], v[110:113]
	v_mfma_f32_16x16x128_f8f6f4 v[106:109], v[26:33], v[226:233], v[106:109]
	v_mfma_f32_16x16x128_f8f6f4 v[102:105], v[18:25], v[234:241], v[102:105]
	v_mfma_f32_16x16x128_f8f6f4 v[98:101], v[26:33], v[234:241], v[98:101]
	s_setprio 2
	s_barrier
	s_add_i32 s55, s92, s45
	v_lshl_add_u64 v[174:175], s[70:71], 0, v[170:171]
	s_mov_b32 m0, s55
	ds_read_b128 v[218:221], v216 offset:16384
	ds_read_b128 v[222:225], v216 offset:17408
	ds_read_b128 v[226:229], v216 offset:18432
	ds_read_b128 v[230:233], v216 offset:19456
	ds_read_b128 v[234:237], v216 offset:20480
	ds_read_b128 v[238:241], v216 offset:21504
	ds_read_b128 v[242:245], v216 offset:22528
	ds_read_b128 v[246:249], v216 offset:23552
	global_load_lds_dwordx4 v[174:175], off
	s_add_i32 m0, s55, 0x2000
	s_add_u32 s90, s70, 0x80000
	v_lshl_add_u64 v[176:177], s[70:71], 0, v[166:167]
	s_addc_u32 s91, s71, 0
	s_add_i32 s5, s5, s45
	global_load_lds_dwordx4 v[176:177], off
	v_lshl_add_u64 v[178:179], s[90:91], 0, v[170:171]
	s_mov_b32 m0, s5
	v_lshl_add_u64 v[180:181], s[72:73], 0, v[168:169]
	global_load_lds_dwordx4 v[178:179], off
	v_lshl_add_u64 v[178:179], s[90:91], 0, v[166:167]
	s_add_i32 m0, s5, 0x2000
	s_nop 0
	global_load_lds_dwordx4 v[178:179], off
	v_lshl_add_u64 v[178:179], s[72:73], 0, v[172:173]
	s_mov_b32 m0, s19
	s_nop 0
	global_load_lds_dwordx4 v[178:179], off
	s_mov_b32 m0, s47
	s_nop 0
	global_load_lds_dwordx4 v[180:181], off
	s_waitcnt vmcnt(8)
	s_waitcnt lgkmcnt(0)
	s_barrier
	s_setprio 1
	s_waitcnt lgkmcnt(0)
	v_mfma_f32_16x16x128_f8f6f4 v[94:97], v[2:9], v[218:225], v[94:97]
	v_mfma_f32_16x16x128_f8f6f4 v[90:93], v[10:17], v[218:225], v[90:93]
	v_mfma_f32_16x16x128_f8f6f4 v[86:89], v[2:9], v[226:233], v[86:89]
	v_mfma_f32_16x16x128_f8f6f4 v[82:85], v[10:17], v[226:233], v[82:85]
	v_mfma_f32_16x16x128_f8f6f4 v[78:81], v[2:9], v[234:241], v[78:81]
	v_mfma_f32_16x16x128_f8f6f4 v[74:77], v[10:17], v[234:241], v[74:77]
	v_mfma_f32_16x16x128_f8f6f4 v[70:73], v[2:9], v[242:249], v[70:73]
	v_mfma_f32_16x16x128_f8f6f4 v[66:69], v[10:17], v[242:249], v[66:69]
	s_setprio 0
	s_setprio 1
	v_mfma_f32_16x16x128_f8f6f4 v[62:65], v[18:25], v[218:225], v[62:65]
	v_mfma_f32_16x16x128_f8f6f4 v[58:61], v[26:33], v[218:225], v[58:61]
	v_mfma_f32_16x16x128_f8f6f4 v[54:57], v[18:25], v[226:233], v[54:57]
	v_mfma_f32_16x16x128_f8f6f4 v[50:53], v[26:33], v[226:233], v[50:53]
	v_mfma_f32_16x16x128_f8f6f4 v[46:49], v[18:25], v[234:241], v[46:49]
	v_mfma_f32_16x16x128_f8f6f4 v[42:45], v[26:33], v[234:241], v[42:45]
	v_mfma_f32_16x16x128_f8f6f4 v[38:41], v[18:25], v[242:249], v[38:41]
	v_mfma_f32_16x16x128_f8f6f4 v[34:37], v[26:33], v[242:249], v[34:37]
	s_setprio 2
	s_barrier
; #define PG8_STAGE(bufoff, gbase, voff) do { if constexpr (DIAG >= 1) break; _Pragma("unroll") for (int _i = 0; _i < 2; ++_i) \
;         __builtin_amdgcn_global_load_lds((const unsigned*)((const char*)(gbase) + (voff)[_i]), (PG8_LAS unsigned*)(lds + (bufoff) + ldsw + _i * 8192), 16, 0, 0); } while (0)
; #define PG8_LDA(dst, b, h) do { if constexpr (DIAG == 2 || DIAG == 3) break; _Pragma("unroll") for (int m = 0; m < 4; ++m) _Pragma("unroll") for (int k = 0; k < 2; ++k) dst[m][k] = *(const PG8_LAS bf16x8*)(lds + PG8_SA(b, h) + aoff + m * 2048 + k * 1024); } while (0)
; #define PG8_LDB(dst, b, h) do { if constexpr (DIAG == 2 || DIAG == 3) break; _Pragma("unroll") for (int n = 0; n < 2; ++n) _Pragma("unroll") for (int k = 0; k < 2; ++k) dst[n][k] = *(const PG8_LAS bf16x8*)(lds + PG8_SB(b, h) + boff + n * 2048 + k * 1024); } while (0)
; #define PG8_WAIT_V(n) asm volatile("s_waitcnt vmcnt(" #n ")" ::: "memory")
; #define PG8_WAIT_L(n) asm volatile("s_waitcnt lgkmcnt(" #n ")" ::: "memory")
; #define PG8_BAR __builtin_amdgcn_s_barrier()
; #define PG8_LP_ON __builtin_amdgcn_s_setprio(PG8_LOADPRIO)
; #define PG8_LP_OFF __builtin_amdgcn_s_setprio(0)
; #define PG8_LP_ON do {} while (0)
; #define PG8_LP_OFF do {} while (0)
;     ...
;             if constexpr (SP2) {
;             PG8_LP_ON; PG8_LDB(B0, 0, 0); PG8_LDB(B1, 0, 1); PG8_SCHED; PG8_LDA(At, 0, 0); PG8_STAGE(PG8_SA(1, 1), a1 + hstep, voffA);
;             PG8_LP_OFF; PG8_WAIT_V(8); PG8_WAIT_L(0); PG8_BAR; PG8_MMA(0, 0, At, B0); PG8_MMA(0, 1, At, B1); PG8_BAR; PG8_SCHED;
;             PG8_LP_ON; PG8_LDA(At, 0, 1); PG8_STAGE(PG8_SB(0, 0), b2, voffB); PG8_STAGE(PG8_SB(0, 1), b2 + hstep, voffB); PG8_STAGE(PG8_SA(0, 0), a2, voffA);
;             PG8_LP_OFF; PG8_WAIT_V(8); PG8_WAIT_L(0); PG8_BAR; PG8_MMA(1, 0, At, B0); PG8_MMA(1, 1, At, B1); PG8_BAR; PG8_SCHED;
;             PG8_LP_ON; PG8_LDB(B0, 1, 0); PG8_LDB(B1, 1, 1); PG8_SCHED; PG8_LDA(At, 1, 0); PG8_STAGE(PG8_SA(0, 1), a2 + hstep, voffA);
;             PG8_LP_OFF; PG8_WAIT_V(8); PG8_WAIT_L(0); PG8_BAR; PG8_MMA(0, 0, At, B0); PG8_MMA(0, 1, At, B1); PG8_BAR; PG8_SCHED;
;             PG8_LP_ON; PG8_LDA(At, 1, 1); PG8_STAGE(PG8_SB(1, 0), b3, voffB); PG8_STAGE(PG8_SB(1, 1), b3 + hstep, voffB); PG8_STAGE(PG8_SA(1, 0), a3, voffA);
;             PG8_LP_OFF; PG8_WAIT_V(8); PG8_WAIT_L(0); PG8_BAR; PG8_MMA(1, 0, At, B0); PG8_MMA(1, 1, At, B1); PG8_BAR; PG8_SCHED;
	s_add_i32 s5, 0, 0x18000
	s_add_i32 s55, 0, 0x1c000
	v_add_u32_e32 v2, s5, v184
	v_add_u32_e32 v6, s55, v184
	ds_read_b128 v[26:29], v2
	ds_read_b128 v[30:33], v2 offset:1024
	ds_read_b128 v[18:21], v2 offset:2048
	ds_read_b128 v[22:25], v2 offset:3072
	ds_read_b128 v[10:13], v6
	ds_read_b128 v[14:17], v6 offset:1024
	ds_read_b128 v[2:5], v6 offset:2048
	ds_read_b128 v[6:9], v6 offset:3072
	s_add_u32 s72, s72, 0x80000
	s_addc_u32 s73, s73, 0
	s_mov_b32 m0, s74
	v_lshl_add_u64 v[250:251], s[72:73], 0, v[172:173]
	ds_read_b128 v[218:221], v216 offset:32768
	ds_read_b128 v[222:225], v216 offset:33792
	ds_read_b128 v[226:229], v216 offset:34816
	ds_read_b128 v[230:233], v216 offset:35840
	ds_read_b128 v[234:237], v216 offset:36864
	ds_read_b128 v[238:241], v216 offset:37888
	ds_read_b128 v[242:245], v216 offset:38912
	ds_read_b128 v[246:249], v216 offset:39936
	global_load_lds_dwordx4 v[250:251], off
	v_lshl_add_u64 v[250:251], s[72:73], 0, v[168:169]
	s_mov_b32 m0, s75
	s_nop 0
	global_load_lds_dwordx4 v[250:251], off
	s_waitcnt vmcnt(8)
	s_waitcnt lgkmcnt(0)
	s_barrier
	s_setprio 1
	s_waitcnt lgkmcnt(0)
	v_mfma_f32_16x16x128_f8f6f4 v[158:161], v[26:33], v[218:225], v[158:161]
	v_mfma_f32_16x16x128_f8f6f4 v[154:157], v[18:25], v[218:225], v[154:157]
	v_mfma_f32_16x16x128_f8f6f4 v[150:153], v[26:33], v[226:233], v[150:153]
	v_mfma_f32_16x16x128_f8f6f4 v[146:149], v[18:25], v[226:233], v[146:149]
	v_mfma_f32_16x16x128_f8f6f4 v[142:145], v[26:33], v[234:241], v[142:145]
	v_mfma_f32_16x16x128_f8f6f4 v[138:141], v[18:25], v[234:241], v[138:141]
	v_mfma_f32_16x16x128_f8f6f4 v[134:137], v[26:33], v[242:249], v[134:137]
	v_mfma_f32_16x16x128_f8f6f4 v[130:133], v[18:25], v[242:249], v[130:133]
	s_setprio 0
	s_setprio 1
	v_mfma_f32_16x16x128_f8f6f4 v[126:129], v[10:17], v[218:225], v[126:129]
	v_mfma_f32_16x16x128_f8f6f4 v[122:125], v[2:9], v[218:225], v[122:125]
	v_mfma_f32_16x16x128_f8f6f4 v[118:121], v[10:17], v[226:233], v[118:121]
	v_mfma_f32_16x16x128_f8f6f4 v[114:117], v[2:9], v[226:233], v[114:117]
	v_mfma_f32_16x16x128_f8f6f4 v[110:113], v[10:17], v[234:241], v[110:113]
	v_mfma_f32_16x16x128_f8f6f4 v[106:109], v[2:9], v[234:241], v[106:109]
	v_mfma_f32_16x16x128_f8f6f4 v[102:105], v[10:17], v[242:249], v[102:105]
	v_mfma_f32_16x16x128_f8f6f4 v[98:101], v[2:9], v[242:249], v[98:101]
	s_setprio 2
	s_barrier
	s_add_i32 s5, s5, s45
	v_lshl_add_u64 v[174:175], v[174:175], 0, s[40:41]
	s_mov_b32 m0, s5
	ds_read_b128 v[218:221], v216 offset:49152
	ds_read_b128 v[222:225], v216 offset:50176
	ds_read_b128 v[226:229], v216 offset:51200
	ds_read_b128 v[230:233], v216 offset:52224
	ds_read_b128 v[234:237], v216 offset:53248
	ds_read_b128 v[238:241], v216 offset:54272
	ds_read_b128 v[242:245], v216 offset:55296
	ds_read_b128 v[246:249], v216 offset:56320
	global_load_lds_dwordx4 v[174:175], off
	s_add_i32 m0, s5, 0x2000
	s_add_u32 s70, s70, 0x80080
	v_lshl_add_u64 v[174:175], v[176:177], 0, s[40:41]
	s_addc_u32 s71, s71, 0
	s_add_i32 s5, s55, s45
	global_load_lds_dwordx4 v[174:175], off
	v_lshl_add_u64 v[174:175], s[70:71], 0, v[170:171]
	s_mov_b32 m0, s5
	s_nop 0
	global_load_lds_dwordx4 v[174:175], off
	v_lshl_add_u64 v[174:175], s[70:71], 0, v[166:167]
	s_add_i32 m0, s5, 0x2000
	s_nop 0
	global_load_lds_dwordx4 v[174:175], off
	v_lshl_add_u64 v[174:175], v[178:179], 0, s[40:41]
	s_mov_b32 m0, s82
	s_nop 0
	global_load_lds_dwordx4 v[174:175], off
	v_lshl_add_u64 v[174:175], v[180:181], 0, s[40:41]
	s_mov_b32 m0, s83
	s_nop 0
	global_load_lds_dwordx4 v[174:175], off
	s_waitcnt vmcnt(8)
	s_waitcnt lgkmcnt(0)
	s_barrier
	s_setprio 1
	s_waitcnt lgkmcnt(0)
	v_mfma_f32_16x16x128_f8f6f4 v[94:97], v[26:33], v[218:225], v[94:97]
	v_mfma_f32_16x16x128_f8f6f4 v[90:93], v[18:25], v[218:225], v[90:93]
	v_mfma_f32_16x16x128_f8f6f4 v[86:89], v[26:33], v[226:233], v[86:89]
	v_mfma_f32_16x16x128_f8f6f4 v[82:85], v[18:25], v[226:233], v[82:85]
	v_mfma_f32_16x16x128_f8f6f4 v[78:81], v[26:33], v[234:241], v[78:81]
	v_mfma_f32_16x16x128_f8f6f4 v[74:77], v[18:25], v[234:241], v[74:77]
	v_mfma_f32_16x16x128_f8f6f4 v[70:73], v[26:33], v[242:249], v[70:73]
	v_mfma_f32_16x16x128_f8f6f4 v[66:69], v[18:25], v[242:249], v[66:69]
	s_setprio 0
	s_setprio 1
	v_mfma_f32_16x16x128_f8f6f4 v[62:65], v[10:17], v[218:225], v[62:65]
	v_mfma_f32_16x16x128_f8f6f4 v[58:61], v[2:9], v[218:225], v[58:61]
	v_mfma_f32_16x16x128_f8f6f4 v[54:57], v[10:17], v[226:233], v[54:57]
	v_mfma_f32_16x16x128_f8f6f4 v[50:53], v[2:9], v[226:233], v[50:53]
	v_mfma_f32_16x16x128_f8f6f4 v[46:49], v[10:17], v[234:241], v[46:49]
	v_mfma_f32_16x16x128_f8f6f4 v[42:45], v[2:9], v[234:241], v[42:45]
	v_mfma_f32_16x16x128_f8f6f4 v[38:41], v[10:17], v[242:249], v[38:41]
	v_mfma_f32_16x16x128_f8f6f4 v[34:37], v[2:9], v[242:249], v[34:37]
	s_setprio 2
	s_barrier
	s_cmp_ge_i32 s4, s79
	s_mov_b32 s55, s4
	s_cbranch_scc0 .LBB0_918

; #define PG8_STAGE(bufoff, gbase, voff) do { if constexpr (DIAG >= 1) break; _Pragma("unroll") for (int _i = 0; _i < 2; ++_i) \
;         __builtin_amdgcn_global_load_lds((const unsigned*)((const char*)(gbase) + (voff)[_i]), (PG8_LAS unsigned*)(lds + (bufoff) + ldsw + _i * 8192), 16, 0, 0); } while (0)
; #define PG8_LDA(dst, b, h) do { if constexpr (DIAG == 2 || DIAG == 3) break; _Pragma("unroll") for (int m = 0; m < 4; ++m) _Pragma("unroll") for (int k = 0; k < 2; ++k) dst[m][k] = *(const PG8_LAS bf16x8*)(lds + PG8_SA(b, h) + aoff + m * 2048 + k * 1024); } while (0)
; #define PG8_WAIT_V(n) asm volatile("s_waitcnt vmcnt(" #n ")" ::: "memory")
; #define PG8_WAIT_L(n) asm volatile("s_waitcnt lgkmcnt(" #n ")" ::: "memory")
; #define PG8_BAR __builtin_amdgcn_s_barrier()
; #define PG8_LP_OFF __builtin_amdgcn_s_setprio(0)
;     ...
;         for (int t = kb; t < ke; t += 2) {
;             const bool last = (t == ke - 2);
;             const char* a1 = cA + (size_t)(t + 1) * kstep;
;             const char* a2 = last ? nA : cA + (size_t)(t + 2) * kstep; const char* b2 = last ? nB : cB + (size_t)(t + 2) * kstep;
;             const char* a3 = a2 + kstep; const char* b3 = b2 + kstep;
;             if (last && has_next) S.a_ready(nxt);
;             if constexpr (SP2) {
;             PG8_LP_ON; PG8_LDB(B0, 0, 0); PG8_LDB(B1, 0, 1); PG8_SCHED; PG8_LDA(At, 0, 0); PG8_STAGE(PG8_SA(1, 1), a1 + hstep, voffA);
;             PG8_LP_OFF; PG8_WAIT_V(8); PG8_WAIT_L(0); PG8_BAR; PG8_MMA(0, 0, At, B0); PG8_MMA(0, 1, At, B1); PG8_BAR; PG8_SCHED;
;             PG8_LP_ON; PG8_LDA(At, 0, 1); PG8_STAGE(PG8_SB(0, 0), b2, voffB); PG8_STAGE(PG8_SB(0, 1), b2 + hstep, voffB); PG8_STAGE(PG8_SA(0, 0), a2, voffA);
;             PG8_LP_OFF; PG8_WAIT_V(8); PG8_WAIT_L(0); PG8_BAR; PG8_MMA(1, 0, At, B0); PG8_MMA(1, 1, At, B1); PG8_BAR; PG8_SCHED;
;             PG8_LP_ON; PG8_LDB(B0, 1, 0); PG8_LDB(B1, 1, 1); PG8_SCHED; PG8_LDA(At, 1, 0); PG8_STAGE(PG8_SA(0, 1), a2 + hstep, voffA);
;             PG8_LP_OFF; PG8_WAIT_V(8); PG8_WAIT_L(0); PG8_BAR; PG8_MMA(0, 0, At, B0); PG8_MMA(0, 1, At, B1); PG8_BAR; PG8_SCHED;
;             PG8_LP_ON; PG8_LDA(At, 1, 1); PG8_STAGE(PG8_SB(1, 0), b3, voffB); PG8_STAGE(PG8_SB(1, 1), b3 + hstep, voffB); PG8_STAGE(PG8_SA(1, 0), a3, voffA);
;             PG8_LP_OFF; PG8_WAIT_V(8); PG8_WAIT_L(0); PG8_BAR; PG8_MMA(1, 0, At, B0); PG8_MMA(1, 1, At, B1); PG8_BAR; PG8_SCHED;
.LBB0_1034:
	s_add_i32 s6, s8, 1
	s_ashr_i32 s7, s6, 31
	s_lshl_b64 s[88:89], s[6:7], 7
	s_add_i32 s6, s8, 2
	s_ashr_i32 s7, s6, 31
	s_lshl_b64 s[60:61], s[6:7], 7
	s_add_u32 s7, s24, s60
	s_addc_u32 s9, s25, s61
	s_add_u32 s90, s22, s60
	s_addc_u32 s91, s23, s61
	s_add_i32 s92, 0, 0x10000
	s_cmp_eq_u32 s87, s8
	s_cselect_b32 s61, s26, s9
	s_cselect_b32 s60, s19, s7
	s_cselect_b32 s9, s47, s91
	s_cselect_b32 s8, s27, s90
	s_add_i32 s7, 0, 0x14000
	v_add_u32_e32 v14, s92, v181
	v_add_u32_e32 v30, s7, v181
	ds_read_b128 v[2:5], v14
	ds_read_b128 v[6:9], v14 offset:1024
	ds_read_b128 v[10:13], v14 offset:2048
	ds_read_b128 v[14:17], v14 offset:3072
	ds_read_b128 v[18:21], v30
	ds_read_b128 v[22:25], v30 offset:1024
	ds_read_b128 v[26:29], v30 offset:2048
	ds_read_b128 v[30:33], v30 offset:3072
	s_add_u32 s88, s24, s88
	s_addc_u32 s89, s25, s89
	s_add_u32 s88, s88, 0x158000
	s_addc_u32 s89, s89, 0
	v_lshl_add_u64 v[238:239], s[88:89], 0, v[166:167]
	s_add_i32 m0, s66, 0xc000
	ds_read_b128 v[172:175], v213
	ds_read_b128 v[176:179], v213 offset:1024
	ds_read_b128 v[214:217], v213 offset:2048
	ds_read_b128 v[218:221], v213 offset:3072
	ds_read_b128 v[222:225], v213 offset:4096
	ds_read_b128 v[226:229], v213 offset:5120
	ds_read_b128 v[230:233], v213 offset:6144
	ds_read_b128 v[234:237], v213 offset:7168
	global_load_lds_dwordx4 v[238:239], off
	v_lshl_add_u64 v[238:239], s[88:89], 0, v[168:169]
	s_add_i32 m0, s66, 0xe000
	s_nop 0
	global_load_lds_dwordx4 v[238:239], off
	s_waitcnt vmcnt(8)
	s_waitcnt lgkmcnt(0)
	s_barrier
	s_setprio 1
	s_waitcnt lgkmcnt(0)
	v_mfma_f32_16x16x128_f8f6f4 v[158:161], v[2:9], v[172:179], v[158:161]
	v_mfma_f32_16x16x128_f8f6f4 v[154:157], v[10:17], v[172:179], v[154:157]
	v_mfma_f32_16x16x128_f8f6f4 v[150:153], v[2:9], v[214:221], v[150:153]
	v_mfma_f32_16x16x128_f8f6f4 v[146:149], v[10:17], v[214:221], v[146:149]
	v_mfma_f32_16x16x128_f8f6f4 v[142:145], v[2:9], v[222:229], v[142:145]
	v_mfma_f32_16x16x128_f8f6f4 v[138:141], v[10:17], v[222:229], v[138:141]
	v_mfma_f32_16x16x128_f8f6f4 v[134:137], v[2:9], v[230:237], v[134:137]
	v_mfma_f32_16x16x128_f8f6f4 v[130:133], v[10:17], v[230:237], v[130:133]
	s_setprio 0
	s_setprio 1
	v_mfma_f32_16x16x128_f8f6f4 v[126:129], v[18:25], v[172:179], v[126:129]
	v_mfma_f32_16x16x128_f8f6f4 v[122:125], v[26:33], v[172:179], v[122:125]
	v_mfma_f32_16x16x128_f8f6f4 v[118:121], v[18:25], v[214:221], v[118:121]
	v_mfma_f32_16x16x128_f8f6f4 v[114:117], v[26:33], v[214:221], v[114:117]
	v_mfma_f32_16x16x128_f8f6f4 v[110:113], v[18:25], v[222:229], v[110:113]
	v_mfma_f32_16x16x128_f8f6f4 v[106:109], v[26:33], v[222:229], v[106:109]
	v_mfma_f32_16x16x128_f8f6f4 v[102:105], v[18:25], v[230:237], v[102:105]
	v_mfma_f32_16x16x128_f8f6f4 v[98:101], v[26:33], v[230:237], v[98:101]
	s_setprio 2
	s_barrier
	s_add_i32 s88, s92, s65
	v_lshl_add_u64 v[172:173], s[8:9], 0, v[166:167]
	s_mov_b32 m0, s88
	ds_read_b128 v[214:217], v213 offset:16384
	ds_read_b128 v[218:221], v213 offset:17408
	ds_read_b128 v[222:225], v213 offset:18432
	ds_read_b128 v[226:229], v213 offset:19456
	ds_read_b128 v[230:233], v213 offset:20480
	ds_read_b128 v[234:237], v213 offset:21504
	ds_read_b128 v[238:241], v213 offset:22528
	ds_read_b128 v[242:245], v213 offset:23552
	global_load_lds_dwordx4 v[172:173], off
	s_add_i32 m0, s88, 0x2000
	s_add_u32 s88, s8, 0x158000
	v_lshl_add_u64 v[174:175], s[8:9], 0, v[168:169]
	s_addc_u32 s89, s9, 0
	s_add_i32 s7, s7, s65
	global_load_lds_dwordx4 v[174:175], off
	v_lshl_add_u64 v[176:177], s[88:89], 0, v[166:167]
	s_mov_b32 m0, s7
	v_lshl_add_u64 v[178:179], s[60:61], 0, v[168:169]
	global_load_lds_dwordx4 v[176:177], off
	v_lshl_add_u64 v[176:177], s[88:89], 0, v[168:169]
	s_add_i32 m0, s7, 0x2000
	s_nop 0
	global_load_lds_dwordx4 v[176:177], off
	v_lshl_add_u64 v[176:177], s[60:61], 0, v[166:167]
	s_mov_b32 m0, s66
	s_nop 0
	global_load_lds_dwordx4 v[176:177], off
	s_mov_b32 m0, s67
	s_nop 0
	global_load_lds_dwordx4 v[178:179], off
	s_waitcnt vmcnt(8)
	s_waitcnt lgkmcnt(0)
	s_barrier
	s_setprio 1
	s_waitcnt lgkmcnt(0)
	v_mfma_f32_16x16x128_f8f6f4 v[94:97], v[2:9], v[214:221], v[94:97]
	v_mfma_f32_16x16x128_f8f6f4 v[90:93], v[10:17], v[214:221], v[90:93]
	v_mfma_f32_16x16x128_f8f6f4 v[86:89], v[2:9], v[222:229], v[86:89]
	v_mfma_f32_16x16x128_f8f6f4 v[82:85], v[10:17], v[222:229], v[82:85]
	v_mfma_f32_16x16x128_f8f6f4 v[78:81], v[2:9], v[230:237], v[78:81]
	v_mfma_f32_16x16x128_f8f6f4 v[74:77], v[10:17], v[230:237], v[74:77]
	v_mfma_f32_16x16x128_f8f6f4 v[70:73], v[2:9], v[238:245], v[70:73]
	v_mfma_f32_16x16x128_f8f6f4 v[66:69], v[10:17], v[238:245], v[66:69]
	s_setprio 0
	s_setprio 1
	v_mfma_f32_16x16x128_f8f6f4 v[62:65], v[18:25], v[214:221], v[62:65]
	v_mfma_f32_16x16x128_f8f6f4 v[58:61], v[26:33], v[214:221], v[58:61]
	v_mfma_f32_16x16x128_f8f6f4 v[54:57], v[18:25], v[222:229], v[54:57]
	v_mfma_f32_16x16x128_f8f6f4 v[50:53], v[26:33], v[222:229], v[50:53]
	v_mfma_f32_16x16x128_f8f6f4 v[46:49], v[18:25], v[230:237], v[46:49]
	v_mfma_f32_16x16x128_f8f6f4 v[42:45], v[26:33], v[230:237], v[42:45]
	v_mfma_f32_16x16x128_f8f6f4 v[38:41], v[18:25], v[238:245], v[38:41]
	v_mfma_f32_16x16x128_f8f6f4 v[34:37], v[26:33], v[238:245], v[34:37]
	s_setprio 2
	s_barrier
; #define PG8_STAGE(bufoff, gbase, voff) do { if constexpr (DIAG >= 1) break; _Pragma("unroll") for (int _i = 0; _i < 2; ++_i) \
;         __builtin_amdgcn_global_load_lds((const unsigned*)((const char*)(gbase) + (voff)[_i]), (PG8_LAS unsigned*)(lds + (bufoff) + ldsw + _i * 8192), 16, 0, 0); } while (0)
; #define PG8_LDA(dst, b, h) do { if constexpr (DIAG == 2 || DIAG == 3) break; _Pragma("unroll") for (int m = 0; m < 4; ++m) _Pragma("unroll") for (int k = 0; k < 2; ++k) dst[m][k] = *(const PG8_LAS bf16x8*)(lds + PG8_SA(b, h) + aoff + m * 2048 + k * 1024); } while (0)
; #define PG8_LDB(dst, b, h) do { if constexpr (DIAG == 2 || DIAG == 3) break; _Pragma("unroll") for (int n = 0; n < 2; ++n) _Pragma("unroll") for (int k = 0; k < 2; ++k) dst[n][k] = *(const PG8_LAS bf16x8*)(lds + PG8_SB(b, h) + boff + n * 2048 + k * 1024); } while (0)
; #define PG8_WAIT_V(n) asm volatile("s_waitcnt vmcnt(" #n ")" ::: "memory")
; #define PG8_WAIT_L(n) asm volatile("s_waitcnt lgkmcnt(" #n ")" ::: "memory")
; #define PG8_BAR __builtin_amdgcn_s_barrier()
; #define PG8_LP_ON __builtin_amdgcn_s_setprio(PG8_LOADPRIO)
; #define PG8_LP_OFF __builtin_amdgcn_s_setprio(0)
; #define PG8_LP_ON do {} while (0)
; #define PG8_LP_OFF do {} while (0)
;     ...
;             if constexpr (SP2) {
;             PG8_LP_ON; PG8_LDB(B0, 0, 0); PG8_LDB(B1, 0, 1); PG8_SCHED; PG8_LDA(At, 0, 0); PG8_STAGE(PG8_SA(1, 1), a1 + hstep, voffA);
;             PG8_LP_OFF; PG8_WAIT_V(8); PG8_WAIT_L(0); PG8_BAR; PG8_MMA(0, 0, At, B0); PG8_MMA(0, 1, At, B1); PG8_BAR; PG8_SCHED;
;             PG8_LP_ON; PG8_LDA(At, 0, 1); PG8_STAGE(PG8_SB(0, 0), b2, voffB); PG8_STAGE(PG8_SB(0, 1), b2 + hstep, voffB); PG8_STAGE(PG8_SA(0, 0), a2, voffA);
;             PG8_LP_OFF; PG8_WAIT_V(8); PG8_WAIT_L(0); PG8_BAR; PG8_MMA(1, 0, At, B0); PG8_MMA(1, 1, At, B1); PG8_BAR; PG8_SCHED;
;             PG8_LP_ON; PG8_LDB(B0, 1, 0); PG8_LDB(B1, 1, 1); PG8_SCHED; PG8_LDA(At, 1, 0); PG8_STAGE(PG8_SA(0, 1), a2 + hstep, voffA);
;             PG8_LP_OFF; PG8_WAIT_V(8); PG8_WAIT_L(0); PG8_BAR; PG8_MMA(0, 0, At, B0); PG8_MMA(0, 1, At, B1); PG8_BAR; PG8_SCHED;
;             PG8_LP_ON; PG8_LDA(At, 1, 1); PG8_STAGE(PG8_SB(1, 0), b3, voffB); PG8_STAGE(PG8_SB(1, 1), b3 + hstep, voffB); PG8_STAGE(PG8_SA(1, 0), a3, voffA);
;             PG8_LP_OFF; PG8_WAIT_V(8); PG8_WAIT_L(0); PG8_BAR; PG8_MMA(1, 0, At, B0); PG8_MMA(1, 1, At, B1); PG8_BAR; PG8_SCHED;
	s_add_i32 s7, 0, 0x18000
	s_add_i32 s88, 0, 0x1c000
	v_add_u32_e32 v2, s7, v181
	v_add_u32_e32 v6, s88, v181
	ds_read_b128 v[26:29], v2
	ds_read_b128 v[30:33], v2 offset:1024
	ds_read_b128 v[18:21], v2 offset:2048
	ds_read_b128 v[22:25], v2 offset:3072
	ds_read_b128 v[10:13], v6
	ds_read_b128 v[14:17], v6 offset:1024
	ds_read_b128 v[2:5], v6 offset:2048
	ds_read_b128 v[6:9], v6 offset:3072
	s_add_u32 s60, s60, 0x158000
	s_addc_u32 s61, s61, 0
	s_mov_b32 m0, s70
	v_lshl_add_u64 v[246:247], s[60:61], 0, v[166:167]
	ds_read_b128 v[214:217], v213 offset:32768
	ds_read_b128 v[218:221], v213 offset:33792
	ds_read_b128 v[222:225], v213 offset:34816
	ds_read_b128 v[226:229], v213 offset:35840
	ds_read_b128 v[230:233], v213 offset:36864
	ds_read_b128 v[234:237], v213 offset:37888
	ds_read_b128 v[238:241], v213 offset:38912
	ds_read_b128 v[242:245], v213 offset:39936
	global_load_lds_dwordx4 v[246:247], off
	v_lshl_add_u64 v[246:247], s[60:61], 0, v[168:169]
	s_mov_b32 m0, s71
	s_nop 0
	global_load_lds_dwordx4 v[246:247], off
	s_waitcnt vmcnt(8)
	s_waitcnt lgkmcnt(0)
	s_barrier
	s_setprio 1
	s_waitcnt lgkmcnt(0)
	v_mfma_f32_16x16x128_f8f6f4 v[158:161], v[26:33], v[214:221], v[158:161]
	v_mfma_f32_16x16x128_f8f6f4 v[154:157], v[18:25], v[214:221], v[154:157]
	v_mfma_f32_16x16x128_f8f6f4 v[150:153], v[26:33], v[222:229], v[150:153]
	v_mfma_f32_16x16x128_f8f6f4 v[146:149], v[18:25], v[222:229], v[146:149]
	v_mfma_f32_16x16x128_f8f6f4 v[142:145], v[26:33], v[230:237], v[142:145]
	v_mfma_f32_16x16x128_f8f6f4 v[138:141], v[18:25], v[230:237], v[138:141]
	v_mfma_f32_16x16x128_f8f6f4 v[134:137], v[26:33], v[238:245], v[134:137]
	v_mfma_f32_16x16x128_f8f6f4 v[130:133], v[18:25], v[238:245], v[130:133]
	s_setprio 0
	s_setprio 1
	v_mfma_f32_16x16x128_f8f6f4 v[126:129], v[10:17], v[214:221], v[126:129]
	v_mfma_f32_16x16x128_f8f6f4 v[122:125], v[2:9], v[214:221], v[122:125]
	v_mfma_f32_16x16x128_f8f6f4 v[118:121], v[10:17], v[222:229], v[118:121]
	v_mfma_f32_16x16x128_f8f6f4 v[114:117], v[2:9], v[222:229], v[114:117]
	v_mfma_f32_16x16x128_f8f6f4 v[110:113], v[10:17], v[230:237], v[110:113]
	v_mfma_f32_16x16x128_f8f6f4 v[106:109], v[2:9], v[230:237], v[106:109]
	v_mfma_f32_16x16x128_f8f6f4 v[102:105], v[10:17], v[238:245], v[102:105]
	v_mfma_f32_16x16x128_f8f6f4 v[98:101], v[2:9], v[238:245], v[98:101]
	s_setprio 2
	s_barrier
	s_add_i32 s7, s7, s65
	v_lshl_add_u64 v[172:173], v[172:173], 0, s[40:41]
	s_mov_b32 m0, s7
	ds_read_b128 v[214:217], v213 offset:49152
	ds_read_b128 v[218:221], v213 offset:50176
	ds_read_b128 v[222:225], v213 offset:51200
	ds_read_b128 v[226:229], v213 offset:52224
	ds_read_b128 v[230:233], v213 offset:53248
	ds_read_b128 v[234:237], v213 offset:54272
	ds_read_b128 v[238:241], v213 offset:55296
	ds_read_b128 v[242:245], v213 offset:56320
	global_load_lds_dwordx4 v[172:173], off
	s_add_i32 m0, s7, 0x2000
	s_add_u32 s8, s8, 0x158080
	v_lshl_add_u64 v[172:173], v[174:175], 0, s[40:41]
	s_addc_u32 s9, s9, 0
	s_add_i32 s7, s88, s65
	global_load_lds_dwordx4 v[172:173], off
	v_lshl_add_u64 v[172:173], s[8:9], 0, v[166:167]
	s_mov_b32 m0, s7
	s_nop 0
	global_load_lds_dwordx4 v[172:173], off
	v_lshl_add_u64 v[172:173], s[8:9], 0, v[168:169]
	s_add_i32 m0, s7, 0x2000
	s_nop 0
	global_load_lds_dwordx4 v[172:173], off
	v_lshl_add_u64 v[172:173], v[176:177], 0, s[40:41]
	s_mov_b32 m0, s77
	s_nop 0
	global_load_lds_dwordx4 v[172:173], off
	v_lshl_add_u64 v[172:173], v[178:179], 0, s[40:41]
	s_mov_b32 m0, s78
	s_nop 0
	global_load_lds_dwordx4 v[172:173], off
	s_waitcnt vmcnt(8)
	s_waitcnt lgkmcnt(0)
	s_barrier
	s_setprio 1
	s_waitcnt lgkmcnt(0)
	v_mfma_f32_16x16x128_f8f6f4 v[94:97], v[26:33], v[214:221], v[94:97]
	v_mfma_f32_16x16x128_f8f6f4 v[90:93], v[18:25], v[214:221], v[90:93]
	v_mfma_f32_16x16x128_f8f6f4 v[86:89], v[26:33], v[222:229], v[86:89]
	v_mfma_f32_16x16x128_f8f6f4 v[82:85], v[18:25], v[222:229], v[82:85]
	v_mfma_f32_16x16x128_f8f6f4 v[78:81], v[26:33], v[230:237], v[78:81]
	v_mfma_f32_16x16x128_f8f6f4 v[74:77], v[18:25], v[230:237], v[74:77]
	v_mfma_f32_16x16x128_f8f6f4 v[70:73], v[26:33], v[238:245], v[70:73]
	v_mfma_f32_16x16x128_f8f6f4 v[66:69], v[18:25], v[238:245], v[66:69]
	s_setprio 0
	s_setprio 1
	v_mfma_f32_16x16x128_f8f6f4 v[62:65], v[10:17], v[214:221], v[62:65]
	v_mfma_f32_16x16x128_f8f6f4 v[58:61], v[2:9], v[214:221], v[58:61]
	v_mfma_f32_16x16x128_f8f6f4 v[54:57], v[10:17], v[222:229], v[54:57]
	v_mfma_f32_16x16x128_f8f6f4 v[50:53], v[2:9], v[222:229], v[50:53]
	v_mfma_f32_16x16x128_f8f6f4 v[46:49], v[10:17], v[230:237], v[46:49]
	v_mfma_f32_16x16x128_f8f6f4 v[42:45], v[2:9], v[230:237], v[42:45]
	v_mfma_f32_16x16x128_f8f6f4 v[38:41], v[10:17], v[238:245], v[38:41]
	v_mfma_f32_16x16x128_f8f6f4 v[34:37], v[2:9], v[238:245], v[34:37]
	s_setprio 2
	s_barrier
	s_cmp_ge_i32 s6, s64
	s_mov_b32 s8, s6
	s_cbranch_scc0 .LBB0_1034
	v_readlane_b32 s94, v252, 39
	v_readlane_b32 s95, v252, 40
